# GEMM MFMA phase: mid-phase s_setprio 0/1 pair removed (32 MFMAs uninterrupted), on top of k-inner + head trim
# speedup vs baseline: 1.0086x; 1.0038x over previous
; #define PG8_STAGE(bufoff, gbase, voff) do { _Pragma("unroll") for (int _i = 0; _i < 2; ++_i) \
;         __builtin_amdgcn_global_load_lds((const unsigned*)((const char*)(gbase) + (voff)[_i]), (LAS unsigned*)(lds + (bufoff) + ldsw + _i * 8192), 16, 0, 0); } while (0)
; #define PG8_LDA(dst, b, h) do { _Pragma("unroll") for (int m = 0; m < 4; ++m) _Pragma("unroll") for (int k = 0; k < 2; ++k) dst[m][k] = *(const LAS bf16x8*)(lds + PG8_SA(b, h) + aoff + m * 2048 + k * 1024); } while (0)
; #define PG8_LDB(dst, b, h) do { _Pragma("unroll") for (int n = 0; n < 2; ++n) _Pragma("unroll") for (int k = 0; k < 2; ++k) dst[n][k] = *(const LAS bf16x8*)(lds + PG8_SB(b, h) + boff + n * 2048 + k * 1024); } while (0)
; template <class Epi, class Sched, bool ALIGN_EPI = false, bool SP2 = false>
; __device__ __forceinline__ void gemm_phase(LAS unsigned char* lds, const Gemm g, const Sched& S, const Epi& E) {
;     ...
;         for (int t = 0; t < nt; t += 2) {
;             const bool last = (t == nt - 2);
;             const char* a1 = cA + (size_t)(t + 1) * kstep;
;             const char* a2 = last ? nA : cA + (size_t)(t + 2) * kstep; const char* b2 = last ? nB : cB + (size_t)(t + 2) * kstep;
;             const char* a3 = a2 + kstep; const char* b3 = b2 + kstep;
;             if (last && has_next) S.a_ready(nxt);
;             if constexpr (SP2) {
;             PG8_LDB(B0, 0, 0); PG8_LDB(B1, 0, 1); PG8_SCHED; PG8_LDA(At, 0, 0); PG8_STAGE(PG8_SA(1, 1), a1 + hstep, voffA);
;             PG8_WAIT_V(8); PG8_WAIT_L(0); PG8_BAR; PG8_MMA(0, 0, At, B0); PG8_MMA(0, 1, At, B1); PG8_BAR; PG8_SCHED;
;             PG8_LDA(At, 0, 1); PG8_STAGE(PG8_SB(0, 0), b2, voffB); PG8_STAGE(PG8_SB(0, 1), b2 + hstep, voffB); PG8_STAGE(PG8_SA(0, 0), a2, voffA);
;             PG8_WAIT_V(8); PG8_WAIT_L(0); PG8_BAR; PG8_MMA(1, 0, At, B0); PG8_MMA(1, 1, At, B1); PG8_BAR; PG8_SCHED;
;             PG8_LDB(B0, 1, 0); PG8_LDB(B1, 1, 1); PG8_SCHED; PG8_LDA(At, 1, 0); PG8_STAGE(PG8_SA(0, 1), a2 + hstep, voffA);
;             PG8_WAIT_V(8); PG8_WAIT_L(0); PG8_BAR; PG8_MMA(0, 0, At, B0); PG8_MMA(0, 1, At, B1); PG8_BAR; PG8_SCHED;
;             PG8_LDA(At, 1, 1); PG8_STAGE(PG8_SB(1, 0), b3, voffB); PG8_STAGE(PG8_SB(1, 1), b3 + hstep, voffB); PG8_STAGE(PG8_SA(1, 0), a3, voffA);
;             PG8_WAIT_V(8); PG8_WAIT_L(0); PG8_BAR; PG8_MMA(1, 0, At, B0); PG8_MMA(1, 1, At, B1); PG8_BAR; PG8_SCHED;
.LBB0_173:
	s_add_u32 s26, s24, 0xfff80080
	s_addc_u32 s27, s25, -1
	s_add_i32 s45, 0, 0x10000
	s_cmp_eq_u32 s44, 28
	s_cselect_b32 s29, s7, s27
	s_cselect_b32 s28, s8, s26
	v_add_u32_e32 v140, s45, v145
	s_cselect_b32 s27, s17, s43
	s_cselect_b32 s26, s19, s35
	s_add_i32 s47, 0, 0x14000
	ds_read_b128 v[150:153], v140
	ds_read_b128 v[154:157], v140 offset:1024
	ds_read_b128 v[158:161], v140 offset:2048
	ds_read_b128 v[162:165], v140 offset:3072
	v_add_u32_e32 v140, s47, v145
	ds_read_b128 v[166:169], v140
	ds_read_b128 v[170:173], v140 offset:1024
	ds_read_b128 v[174:177], v140 offset:2048
	ds_read_b128 v[178:181], v140 offset:3072
	v_lshl_add_u64 v[140:141], s[24:25], 0, v[136:137]
	s_add_i32 m0, s30, 0xc000
	ds_read_b128 v[182:185], v149
	ds_read_b128 v[194:197], v149 offset:1024
	ds_read_b128 v[198:201], v149 offset:2048
	ds_read_b128 v[202:205], v149 offset:3072
	ds_read_b128 v[206:209], v149 offset:4096
	ds_read_b128 v[210:213], v149 offset:5120
	ds_read_b128 v[214:217], v149 offset:6144
	ds_read_b128 v[218:221], v149 offset:7168
	global_load_lds_dwordx4 v[140:141], off
	v_lshl_add_u64 v[140:141], s[24:25], 0, v[138:139]
	s_add_i32 m0, s30, 0xe000
	s_nop 0
	global_load_lds_dwordx4 v[140:141], off
	s_waitcnt vmcnt(8)
	s_waitcnt lgkmcnt(0)
	s_setprio 1
	s_barrier
	v_mfma_f32_16x16x32_bf16 v[126:129], v[150:153], v[182:185], v[126:129]
	v_mfma_f32_16x16x32_bf16 v[126:129], v[154:157], v[194:197], v[126:129]
	v_mfma_f32_16x16x32_bf16 v[122:125], v[158:161], v[182:185], v[122:125]
	v_mfma_f32_16x16x32_bf16 v[122:125], v[162:165], v[194:197], v[122:125]
	v_mfma_f32_16x16x32_bf16 v[106:109], v[158:161], v[198:201], v[106:109]
	v_mfma_f32_16x16x32_bf16 v[106:109], v[162:165], v[202:205], v[106:109]
	v_mfma_f32_16x16x32_bf16 v[110:113], v[150:153], v[198:201], v[110:113]
	v_mfma_f32_16x16x32_bf16 v[110:113], v[154:157], v[202:205], v[110:113]
	v_mfma_f32_16x16x32_bf16 v[94:97], v[150:153], v[206:209], v[94:97]
	v_mfma_f32_16x16x32_bf16 v[94:97], v[154:157], v[210:213], v[94:97]
	v_mfma_f32_16x16x32_bf16 v[90:93], v[158:161], v[206:209], v[90:93]
	v_mfma_f32_16x16x32_bf16 v[90:93], v[162:165], v[210:213], v[90:93]
	v_mfma_f32_16x16x32_bf16 v[74:77], v[158:161], v[214:217], v[74:77]
	v_mfma_f32_16x16x32_bf16 v[74:77], v[162:165], v[218:221], v[74:77]
	v_mfma_f32_16x16x32_bf16 v[78:81], v[150:153], v[214:217], v[78:81]
	v_mfma_f32_16x16x32_bf16 v[78:81], v[154:157], v[218:221], v[78:81]
	v_mfma_f32_16x16x32_bf16 v[118:121], v[166:169], v[182:185], v[118:121]
	v_mfma_f32_16x16x32_bf16 v[118:121], v[170:173], v[194:197], v[118:121]
	v_mfma_f32_16x16x32_bf16 v[114:117], v[174:177], v[182:185], v[114:117]
	v_mfma_f32_16x16x32_bf16 v[114:117], v[178:181], v[194:197], v[114:117]
	v_mfma_f32_16x16x32_bf16 v[98:101], v[174:177], v[198:201], v[98:101]
	v_mfma_f32_16x16x32_bf16 v[98:101], v[178:181], v[202:205], v[98:101]
	v_mfma_f32_16x16x32_bf16 v[102:105], v[166:169], v[198:201], v[102:105]
	v_mfma_f32_16x16x32_bf16 v[102:105], v[170:173], v[202:205], v[102:105]
	v_mfma_f32_16x16x32_bf16 v[86:89], v[166:169], v[206:209], v[86:89]
	v_mfma_f32_16x16x32_bf16 v[86:89], v[170:173], v[210:213], v[86:89]
	v_mfma_f32_16x16x32_bf16 v[82:85], v[174:177], v[206:209], v[82:85]
	v_mfma_f32_16x16x32_bf16 v[82:85], v[178:181], v[210:213], v[82:85]
	v_mfma_f32_16x16x32_bf16 v[66:69], v[174:177], v[214:217], v[66:69]
	v_mfma_f32_16x16x32_bf16 v[66:69], v[178:181], v[218:221], v[66:69]
	v_mfma_f32_16x16x32_bf16 v[70:73], v[166:169], v[214:217], v[70:73]
	v_mfma_f32_16x16x32_bf16 v[70:73], v[170:173], v[218:221], v[70:73]
	s_setprio 0
	s_barrier
	s_add_i32 s45, s45, s9
	v_lshl_add_u64 v[140:141], s[26:27], 0, v[0:1]
	s_mov_b32 m0, s45
	ds_read_b128 v[182:185], v149 offset:16384
	ds_read_b128 v[194:197], v149 offset:17408
	ds_read_b128 v[198:201], v149 offset:18432
	ds_read_b128 v[202:205], v149 offset:19456
	ds_read_b128 v[206:209], v149 offset:20480
	ds_read_b128 v[210:213], v149 offset:21504
	ds_read_b128 v[214:217], v149 offset:22528
	ds_read_b128 v[218:221], v149 offset:23552
	global_load_lds_dwordx4 v[140:141], off
	s_add_i32 m0, s45, 0x2000
	s_add_u32 s48, s26, 0x80000
	v_lshl_add_u64 v[186:187], s[26:27], 0, v[130:131]
	s_addc_u32 s49, s27, 0
	s_add_i32 s45, s47, s9
	global_load_lds_dwordx4 v[186:187], off
	v_lshl_add_u64 v[188:189], s[48:49], 0, v[0:1]
	s_mov_b32 m0, s45
	v_lshl_add_u64 v[190:191], s[28:29], 0, v[132:133]
	global_load_lds_dwordx4 v[188:189], off
	v_lshl_add_u64 v[188:189], s[48:49], 0, v[130:131]
	s_add_i32 m0, s45, 0x2000
	s_nop 0
	global_load_lds_dwordx4 v[188:189], off
	v_lshl_add_u64 v[188:189], s[28:29], 0, v[134:135]
	s_mov_b32 m0, s30
	s_nop 0
	global_load_lds_dwordx4 v[188:189], off
	s_mov_b32 m0, s31
	s_nop 0
	global_load_lds_dwordx4 v[190:191], off
	s_waitcnt vmcnt(8)
	s_waitcnt lgkmcnt(0)
	s_setprio 1
	s_barrier
; #define PG8_STAGE(bufoff, gbase, voff) do { _Pragma("unroll") for (int _i = 0; _i < 2; ++_i) \
;         __builtin_amdgcn_global_load_lds((const unsigned*)((const char*)(gbase) + (voff)[_i]), (LAS unsigned*)(lds + (bufoff) + ldsw + _i * 8192), 16, 0, 0); } while (0)
; #define PG8_LDA(dst, b, h) do { _Pragma("unroll") for (int m = 0; m < 4; ++m) _Pragma("unroll") for (int k = 0; k < 2; ++k) dst[m][k] = *(const LAS bf16x8*)(lds + PG8_SA(b, h) + aoff + m * 2048 + k * 1024); } while (0)
; #define PG8_LDB(dst, b, h) do { _Pragma("unroll") for (int n = 0; n < 2; ++n) _Pragma("unroll") for (int k = 0; k < 2; ++k) dst[n][k] = *(const LAS bf16x8*)(lds + PG8_SB(b, h) + boff + n * 2048 + k * 1024); } while (0)
; #define PG8_MMA(ai, bj, At, Bt) do { __builtin_amdgcn_s_setprio(1); _Pragma("unroll") for (int m = 0; m < 4; ++m) _Pragma("unroll") for (int n = 0; n < 2; ++n) _Pragma("unroll") for (int k = 0; k < 2; ++k) \
;         acc[ai][bj][m][n] = __builtin_amdgcn_mfma_f32_16x16x32_bf16(Bt[n][k], At[m][k], acc[ai][bj][m][n], 0, 0, 0); __builtin_amdgcn_s_setprio(0); } while (0)
; #define PG8_WAIT_V(n) asm volatile("s_waitcnt vmcnt(" #n ")" ::: "memory")
; #define PG8_WAIT_L(n) asm volatile("s_waitcnt lgkmcnt(" #n ")" ::: "memory")
; #define PG8_BAR __builtin_amdgcn_s_barrier()
; #define PG8_SCHED __builtin_amdgcn_sched_barrier(0)
; template <class Epi, class Sched, bool ALIGN_EPI = false, bool SP2 = false>
; __device__ __forceinline__ void gemm_phase(LAS unsigned char* lds, const Gemm g, const Sched& S, const Epi& E) {
;     ...
;             PG8_WAIT_V(8); PG8_WAIT_L(0); PG8_BAR; PG8_MMA(0, 0, At, B0); PG8_MMA(0, 1, At, B1); PG8_BAR; PG8_SCHED;
;             PG8_LDA(At, 0, 1); PG8_STAGE(PG8_SB(0, 0), b2, voffB); PG8_STAGE(PG8_SB(0, 1), b2 + hstep, voffB); PG8_STAGE(PG8_SA(0, 0), a2, voffA);
;             PG8_WAIT_V(8); PG8_WAIT_L(0); PG8_BAR; PG8_MMA(1, 0, At, B0); PG8_MMA(1, 1, At, B1); PG8_BAR; PG8_SCHED;
;             PG8_LDB(B0, 1, 0); PG8_LDB(B1, 1, 1); PG8_SCHED; PG8_LDA(At, 1, 0); PG8_STAGE(PG8_SA(0, 1), a2 + hstep, voffA);
;             PG8_WAIT_V(8); PG8_WAIT_L(0); PG8_BAR; PG8_MMA(0, 0, At, B0); PG8_MMA(0, 1, At, B1); PG8_BAR; PG8_SCHED;
	v_mfma_f32_16x16x32_bf16 v[62:65], v[150:153], v[182:185], v[62:65]
	v_mfma_f32_16x16x32_bf16 v[62:65], v[154:157], v[194:197], v[62:65]
	v_mfma_f32_16x16x32_bf16 v[58:61], v[158:161], v[182:185], v[58:61]
	v_mfma_f32_16x16x32_bf16 v[58:61], v[162:165], v[194:197], v[58:61]
	v_mfma_f32_16x16x32_bf16 v[42:45], v[158:161], v[198:201], v[42:45]
	v_mfma_f32_16x16x32_bf16 v[42:45], v[162:165], v[202:205], v[42:45]
	v_mfma_f32_16x16x32_bf16 v[46:49], v[150:153], v[198:201], v[46:49]
	v_mfma_f32_16x16x32_bf16 v[46:49], v[154:157], v[202:205], v[46:49]
	v_mfma_f32_16x16x32_bf16 v[30:33], v[150:153], v[206:209], v[30:33]
	v_mfma_f32_16x16x32_bf16 v[30:33], v[154:157], v[210:213], v[30:33]
	v_mfma_f32_16x16x32_bf16 v[26:29], v[158:161], v[206:209], v[26:29]
	v_mfma_f32_16x16x32_bf16 v[26:29], v[162:165], v[210:213], v[26:29]
	v_mfma_f32_16x16x32_bf16 v[10:13], v[158:161], v[214:217], v[10:13]
	v_mfma_f32_16x16x32_bf16 v[10:13], v[162:165], v[218:221], v[10:13]
	v_mfma_f32_16x16x32_bf16 v[14:17], v[150:153], v[214:217], v[14:17]
	v_mfma_f32_16x16x32_bf16 v[14:17], v[154:157], v[218:221], v[14:17]
	v_mfma_f32_16x16x32_bf16 v[54:57], v[166:169], v[182:185], v[54:57]
	v_mfma_f32_16x16x32_bf16 v[54:57], v[170:173], v[194:197], v[54:57]
	v_mfma_f32_16x16x32_bf16 v[50:53], v[174:177], v[182:185], v[50:53]
	v_mfma_f32_16x16x32_bf16 v[50:53], v[178:181], v[194:197], v[50:53]
	v_mfma_f32_16x16x32_bf16 v[34:37], v[174:177], v[198:201], v[34:37]
	v_mfma_f32_16x16x32_bf16 v[34:37], v[178:181], v[202:205], v[34:37]
	v_mfma_f32_16x16x32_bf16 v[38:41], v[166:169], v[198:201], v[38:41]
	v_mfma_f32_16x16x32_bf16 v[38:41], v[170:173], v[202:205], v[38:41]
	v_mfma_f32_16x16x32_bf16 v[22:25], v[166:169], v[206:209], v[22:25]
	v_mfma_f32_16x16x32_bf16 v[22:25], v[170:173], v[210:213], v[22:25]
	v_mfma_f32_16x16x32_bf16 v[18:21], v[174:177], v[206:209], v[18:21]
	v_mfma_f32_16x16x32_bf16 v[18:21], v[178:181], v[210:213], v[18:21]
	v_mfma_f32_16x16x32_bf16 v[2:5], v[174:177], v[214:217], v[2:5]
	v_mfma_f32_16x16x32_bf16 v[2:5], v[178:181], v[218:221], v[2:5]
	v_mfma_f32_16x16x32_bf16 v[6:9], v[166:169], v[214:217], v[6:9]
	v_mfma_f32_16x16x32_bf16 v[6:9], v[170:173], v[218:221], v[6:9]
	s_setprio 0
	s_barrier
	s_add_i32 s45, 0, 0x18000
	v_add_u32_e32 v142, s45, v145
	s_add_i32 s47, 0, 0x1c000
	ds_read_b128 v[150:153], v142
	ds_read_b128 v[154:157], v142 offset:1024
	ds_read_b128 v[158:161], v142 offset:2048
	ds_read_b128 v[162:165], v142 offset:3072
	v_add_u32_e32 v142, s47, v145
	ds_read_b128 v[166:169], v142
	ds_read_b128 v[170:173], v142 offset:1024
	ds_read_b128 v[174:177], v142 offset:2048
	ds_read_b128 v[178:181], v142 offset:3072
	s_add_u32 s28, s28, 0x80000
	s_addc_u32 s29, s29, 0
	s_mov_b32 m0, s38
	v_lshl_add_u64 v[192:193], s[28:29], 0, v[134:135]
	ds_read_b128 v[182:185], v149 offset:32768
	ds_read_b128 v[194:197], v149 offset:33792
	ds_read_b128 v[198:201], v149 offset:34816
	ds_read_b128 v[202:205], v149 offset:35840
	ds_read_b128 v[206:209], v149 offset:36864
	ds_read_b128 v[210:213], v149 offset:37888
	ds_read_b128 v[214:217], v149 offset:38912
	ds_read_b128 v[218:221], v149 offset:39936
	global_load_lds_dwordx4 v[192:193], off
	v_lshl_add_u64 v[192:193], s[28:29], 0, v[132:133]
	s_mov_b32 m0, s39
	s_nop 0
	global_load_lds_dwordx4 v[192:193], off
	s_waitcnt vmcnt(8)
	s_waitcnt lgkmcnt(0)
	s_setprio 1
	s_barrier
	v_mfma_f32_16x16x32_bf16 v[126:129], v[150:153], v[182:185], v[126:129]
	v_mfma_f32_16x16x32_bf16 v[126:129], v[154:157], v[194:197], v[126:129]
	v_mfma_f32_16x16x32_bf16 v[122:125], v[158:161], v[182:185], v[122:125]
	v_mfma_f32_16x16x32_bf16 v[122:125], v[162:165], v[194:197], v[122:125]
	v_mfma_f32_16x16x32_bf16 v[106:109], v[158:161], v[198:201], v[106:109]
	v_mfma_f32_16x16x32_bf16 v[106:109], v[162:165], v[202:205], v[106:109]
	v_mfma_f32_16x16x32_bf16 v[110:113], v[150:153], v[198:201], v[110:113]
	v_mfma_f32_16x16x32_bf16 v[110:113], v[154:157], v[202:205], v[110:113]
	v_mfma_f32_16x16x32_bf16 v[94:97], v[150:153], v[206:209], v[94:97]
	v_mfma_f32_16x16x32_bf16 v[94:97], v[154:157], v[210:213], v[94:97]
	v_mfma_f32_16x16x32_bf16 v[90:93], v[158:161], v[206:209], v[90:93]
	v_mfma_f32_16x16x32_bf16 v[90:93], v[162:165], v[210:213], v[90:93]
	v_mfma_f32_16x16x32_bf16 v[74:77], v[158:161], v[214:217], v[74:77]
	v_mfma_f32_16x16x32_bf16 v[74:77], v[162:165], v[218:221], v[74:77]
	v_mfma_f32_16x16x32_bf16 v[78:81], v[150:153], v[214:217], v[78:81]
	v_mfma_f32_16x16x32_bf16 v[78:81], v[154:157], v[218:221], v[78:81]
	v_mfma_f32_16x16x32_bf16 v[118:121], v[166:169], v[182:185], v[118:121]
	v_mfma_f32_16x16x32_bf16 v[118:121], v[170:173], v[194:197], v[118:121]
	v_mfma_f32_16x16x32_bf16 v[114:117], v[174:177], v[182:185], v[114:117]
	v_mfma_f32_16x16x32_bf16 v[114:117], v[178:181], v[194:197], v[114:117]
	v_mfma_f32_16x16x32_bf16 v[98:101], v[174:177], v[198:201], v[98:101]
	v_mfma_f32_16x16x32_bf16 v[98:101], v[178:181], v[202:205], v[98:101]
	v_mfma_f32_16x16x32_bf16 v[102:105], v[166:169], v[198:201], v[102:105]
	v_mfma_f32_16x16x32_bf16 v[102:105], v[170:173], v[202:205], v[102:105]
	v_mfma_f32_16x16x32_bf16 v[86:89], v[166:169], v[206:209], v[86:89]
	v_mfma_f32_16x16x32_bf16 v[86:89], v[170:173], v[210:213], v[86:89]
	v_mfma_f32_16x16x32_bf16 v[82:85], v[174:177], v[206:209], v[82:85]
	v_mfma_f32_16x16x32_bf16 v[82:85], v[178:181], v[210:213], v[82:85]
	v_mfma_f32_16x16x32_bf16 v[66:69], v[174:177], v[214:217], v[66:69]
	v_mfma_f32_16x16x32_bf16 v[66:69], v[178:181], v[218:221], v[66:69]
	v_mfma_f32_16x16x32_bf16 v[70:73], v[166:169], v[214:217], v[70:73]
	v_mfma_f32_16x16x32_bf16 v[70:73], v[170:173], v[218:221], v[70:73]
	s_setprio 0
	s_barrier
; #define PG8_STAGE(bufoff, gbase, voff) do { _Pragma("unroll") for (int _i = 0; _i < 2; ++_i) \
;         __builtin_amdgcn_global_load_lds((const unsigned*)((const char*)(gbase) + (voff)[_i]), (LAS unsigned*)(lds + (bufoff) + ldsw + _i * 8192), 16, 0, 0); } while (0)
; #define PG8_LDA(dst, b, h) do { _Pragma("unroll") for (int m = 0; m < 4; ++m) _Pragma("unroll") for (int k = 0; k < 2; ++k) dst[m][k] = *(const LAS bf16x8*)(lds + PG8_SA(b, h) + aoff + m * 2048 + k * 1024); } while (0)
; #define PG8_MMA(ai, bj, At, Bt) do { __builtin_amdgcn_s_setprio(1); _Pragma("unroll") for (int m = 0; m < 4; ++m) _Pragma("unroll") for (int n = 0; n < 2; ++n) _Pragma("unroll") for (int k = 0; k < 2; ++k) \
;         acc[ai][bj][m][n] = __builtin_amdgcn_mfma_f32_16x16x32_bf16(Bt[n][k], At[m][k], acc[ai][bj][m][n], 0, 0, 0); __builtin_amdgcn_s_setprio(0); } while (0)
; #define PG8_WAIT_V(n) asm volatile("s_waitcnt vmcnt(" #n ")" ::: "memory")
; #define PG8_WAIT_L(n) asm volatile("s_waitcnt lgkmcnt(" #n ")" ::: "memory")
; #define PG8_BAR __builtin_amdgcn_s_barrier()
; #define PG8_SCHED __builtin_amdgcn_sched_barrier(0)
; template <class Epi, class Sched, bool ALIGN_EPI = false, bool SP2 = false>
; __device__ __forceinline__ void gemm_phase(LAS unsigned char* lds, const Gemm g, const Sched& S, const Epi& E) {
;     ...
;         for (int t = 0; t < nt; t += 2) {
;     ...
;             PG8_WAIT_V(8); PG8_WAIT_L(0); PG8_BAR; PG8_MMA(0, 0, At, B0); PG8_MMA(0, 1, At, B1); PG8_BAR; PG8_SCHED;
;             PG8_LDA(At, 1, 1); PG8_STAGE(PG8_SB(1, 0), b3, voffB); PG8_STAGE(PG8_SB(1, 1), b3 + hstep, voffB); PG8_STAGE(PG8_SA(1, 0), a3, voffA);
;             PG8_WAIT_V(8); PG8_WAIT_L(0); PG8_BAR; PG8_MMA(1, 0, At, B0); PG8_MMA(1, 1, At, B1); PG8_BAR; PG8_SCHED;
;     ...
;         if constexpr (ALIGN_EPI) { if (wr == 0) PG8_BAR; }
	s_add_i32 s28, s45, s9
	v_lshl_add_u64 v[140:141], v[140:141], 0, s[12:13]
	s_mov_b32 m0, s28
	ds_read_b128 v[182:185], v149 offset:49152
	ds_read_b128 v[194:197], v149 offset:50176
	ds_read_b128 v[198:201], v149 offset:51200
	ds_read_b128 v[202:205], v149 offset:52224
	ds_read_b128 v[206:209], v149 offset:53248
	ds_read_b128 v[210:213], v149 offset:54272
	ds_read_b128 v[214:217], v149 offset:55296
	ds_read_b128 v[218:221], v149 offset:56320
	global_load_lds_dwordx4 v[140:141], off
	s_add_i32 m0, s28, 0x2000
	s_add_u32 s26, s26, 0x80080
	v_lshl_add_u64 v[140:141], v[186:187], 0, s[12:13]
	s_addc_u32 s27, s27, 0
	s_add_i32 s28, s47, s9
	global_load_lds_dwordx4 v[140:141], off
	v_lshl_add_u64 v[140:141], s[26:27], 0, v[0:1]
	s_mov_b32 m0, s28
	s_nop 0
	global_load_lds_dwordx4 v[140:141], off
	v_lshl_add_u64 v[140:141], s[26:27], 0, v[130:131]
	s_add_i32 m0, s28, 0x2000
	s_nop 0
	global_load_lds_dwordx4 v[140:141], off
	v_lshl_add_u64 v[140:141], v[188:189], 0, s[12:13]
	s_mov_b32 m0, s40
	s_nop 0
	global_load_lds_dwordx4 v[140:141], off
	v_lshl_add_u64 v[140:141], v[190:191], 0, s[12:13]
	s_mov_b32 m0, s41
	s_nop 0
	global_load_lds_dwordx4 v[140:141], off
	s_waitcnt vmcnt(8)
	s_waitcnt lgkmcnt(0)
	s_setprio 1
	s_barrier
	v_mfma_f32_16x16x32_bf16 v[62:65], v[150:153], v[182:185], v[62:65]
	v_mfma_f32_16x16x32_bf16 v[62:65], v[154:157], v[194:197], v[62:65]
	v_mfma_f32_16x16x32_bf16 v[58:61], v[158:161], v[182:185], v[58:61]
	v_mfma_f32_16x16x32_bf16 v[58:61], v[162:165], v[194:197], v[58:61]
	v_mfma_f32_16x16x32_bf16 v[42:45], v[158:161], v[198:201], v[42:45]
	v_mfma_f32_16x16x32_bf16 v[42:45], v[162:165], v[202:205], v[42:45]
	v_mfma_f32_16x16x32_bf16 v[46:49], v[150:153], v[198:201], v[46:49]
	v_mfma_f32_16x16x32_bf16 v[46:49], v[154:157], v[202:205], v[46:49]
	v_mfma_f32_16x16x32_bf16 v[30:33], v[150:153], v[206:209], v[30:33]
	v_mfma_f32_16x16x32_bf16 v[30:33], v[154:157], v[210:213], v[30:33]
	v_mfma_f32_16x16x32_bf16 v[26:29], v[158:161], v[206:209], v[26:29]
	v_mfma_f32_16x16x32_bf16 v[26:29], v[162:165], v[210:213], v[26:29]
	v_mfma_f32_16x16x32_bf16 v[10:13], v[158:161], v[214:217], v[10:13]
	v_mfma_f32_16x16x32_bf16 v[10:13], v[162:165], v[218:221], v[10:13]
	v_mfma_f32_16x16x32_bf16 v[14:17], v[150:153], v[214:217], v[14:17]
	v_mfma_f32_16x16x32_bf16 v[14:17], v[154:157], v[218:221], v[14:17]
	v_mfma_f32_16x16x32_bf16 v[54:57], v[166:169], v[182:185], v[54:57]
	v_mfma_f32_16x16x32_bf16 v[54:57], v[170:173], v[194:197], v[54:57]
	v_mfma_f32_16x16x32_bf16 v[50:53], v[174:177], v[182:185], v[50:53]
	v_mfma_f32_16x16x32_bf16 v[50:53], v[178:181], v[194:197], v[50:53]
	v_mfma_f32_16x16x32_bf16 v[34:37], v[174:177], v[198:201], v[34:37]
	v_mfma_f32_16x16x32_bf16 v[34:37], v[178:181], v[202:205], v[34:37]
	v_mfma_f32_16x16x32_bf16 v[38:41], v[166:169], v[198:201], v[38:41]
	v_mfma_f32_16x16x32_bf16 v[38:41], v[170:173], v[202:205], v[38:41]
	v_mfma_f32_16x16x32_bf16 v[22:25], v[166:169], v[206:209], v[22:25]
	v_mfma_f32_16x16x32_bf16 v[22:25], v[170:173], v[210:213], v[22:25]
	v_mfma_f32_16x16x32_bf16 v[18:21], v[174:177], v[206:209], v[18:21]
	v_mfma_f32_16x16x32_bf16 v[18:21], v[178:181], v[210:213], v[18:21]
	v_mfma_f32_16x16x32_bf16 v[2:5], v[174:177], v[214:217], v[2:5]
	v_mfma_f32_16x16x32_bf16 v[2:5], v[178:181], v[218:221], v[2:5]
	v_mfma_f32_16x16x32_bf16 v[6:9], v[166:169], v[214:217], v[6:9]
	v_mfma_f32_16x16x32_bf16 v[6:9], v[170:173], v[218:221], v[6:9]
	s_setprio 0
	s_barrier
	s_add_i32 s44, s44, 2
	s_add_u32 s24, s24, 0x100
	s_addc_u32 s25, s25, 0
	s_add_u32 s35, s35, 0x100
	s_addc_u32 s43, s43, 0
	s_cmp_gt_u32 s44, 29
	s_cbranch_scc0 .LBB0_173
	s_and_b64 vcc, exec, s[4:5]
	s_cbranch_vccz .LBB0_176
	s_barrier

; #define PG8_STAGE(bufoff, gbase, voff) do { _Pragma("unroll") for (int _i = 0; _i < 2; ++_i) \
;         __builtin_amdgcn_global_load_lds((const unsigned*)((const char*)(gbase) + (voff)[_i]), (LAS unsigned*)(lds + (bufoff) + ldsw + _i * 8192), 16, 0, 0); } while (0)
; #define PG8_LDA(dst, b, h) do { _Pragma("unroll") for (int m = 0; m < 4; ++m) _Pragma("unroll") for (int k = 0; k < 2; ++k) dst[m][k] = *(const LAS bf16x8*)(lds + PG8_SA(b, h) + aoff + m * 2048 + k * 1024); } while (0)
; #define PG8_LDB(dst, b, h) do { _Pragma("unroll") for (int n = 0; n < 2; ++n) _Pragma("unroll") for (int k = 0; k < 2; ++k) dst[n][k] = *(const LAS bf16x8*)(lds + PG8_SB(b, h) + boff + n * 2048 + k * 1024); } while (0)
; #define PG8_MMA(ai, bj, At, Bt) do { __builtin_amdgcn_s_setprio(1); _Pragma("unroll") for (int m = 0; m < 4; ++m) _Pragma("unroll") for (int n = 0; n < 2; ++n) _Pragma("unroll") for (int k = 0; k < 2; ++k) \
;         acc[ai][bj][m][n] = __builtin_amdgcn_mfma_f32_16x16x32_bf16(Bt[n][k], At[m][k], acc[ai][bj][m][n], 0, 0, 0); __builtin_amdgcn_s_setprio(0); } while (0)
; #define PG8_WAIT_V(n) asm volatile("s_waitcnt vmcnt(" #n ")" ::: "memory")
; #define PG8_WAIT_L(n) asm volatile("s_waitcnt lgkmcnt(" #n ")" ::: "memory")
; #define PG8_BAR __builtin_amdgcn_s_barrier()
; #define PG8_SCHED __builtin_amdgcn_sched_barrier(0)
; template <class Epi, class Sched, bool ALIGN_EPI = false, bool SP2 = false>
; __device__ __forceinline__ void gemm_phase(LAS unsigned char* lds, const Gemm g, const Sched& S, const Epi& E) {
;     ...
;             const bool last = (t == nt - 2);
;             const char* a1 = cA + (size_t)(t + 1) * kstep;
;             const char* a2 = last ? nA : cA + (size_t)(t + 2) * kstep; const char* b2 = last ? nB : cB + (size_t)(t + 2) * kstep;
;             const char* a3 = a2 + kstep; const char* b3 = b2 + kstep;
;             if (last && has_next) S.a_ready(nxt);
;             if constexpr (SP2) {
;             PG8_LDB(B0, 0, 0); PG8_LDB(B1, 0, 1); PG8_SCHED; PG8_LDA(At, 0, 0); PG8_STAGE(PG8_SA(1, 1), a1 + hstep, voffA);
;             PG8_WAIT_V(8); PG8_WAIT_L(0); PG8_BAR; PG8_MMA(0, 0, At, B0); PG8_MMA(0, 1, At, B1); PG8_BAR; PG8_SCHED;
;             PG8_LDA(At, 0, 1); PG8_STAGE(PG8_SB(0, 0), b2, voffB); PG8_STAGE(PG8_SB(0, 1), b2 + hstep, voffB); PG8_STAGE(PG8_SA(0, 0), a2, voffA);
.LBB0_257:
	s_add_u32 s24, s22, 0x100
	s_addc_u32 s25, s23, 0
	s_add_i32 s50, 0, 0x10000
	s_cmpk_eq_i32 s49, 0x54
	s_cselect_b32 s29, s1, s25
	s_cselect_b32 s28, s0, s24
	s_cselect_b32 s27, s21, s48
	s_cselect_b32 s26, s20, s47
	s_add_i32 s51, 0, 0x14000
	v_add_u32_e32 v126, s50, v247
	v_add_u32_e32 v158, s51, v247
	ds_read_b128 v[90:93], v126
	ds_read_b128 v[102:105], v126 offset:1024
	ds_read_b128 v[114:117], v126 offset:2048
	ds_read_b128 v[126:129], v126 offset:3072
	ds_read_b128 v[138:141], v158
	ds_read_b128 v[142:145], v158 offset:1024
	ds_read_b128 v[154:157], v158 offset:2048
	ds_read_b128 v[158:161], v158 offset:3072
	v_lshl_add_u64 v[186:187], s[22:23], 0, v[200:201]
	s_add_i32 m0, s6, 0xc000
	ds_read_b128 v[162:165], v249
	ds_read_b128 v[166:169], v249 offset:1024
	ds_read_b128 v[170:173], v249 offset:2048
	ds_read_b128 v[174:177], v249 offset:3072
	ds_read_b128 v[178:181], v249 offset:4096
	ds_read_b128 v[182:185], v249 offset:5120
	ds_read_b128 v[204:207], v249 offset:6144
	ds_read_b128 v[208:211], v249 offset:7168
	global_load_lds_dwordx4 v[186:187], off
	v_lshl_add_u64 v[186:187], s[22:23], 0, v[202:203]
	s_add_i32 m0, s6, 0xe000
	s_nop 0
	global_load_lds_dwordx4 v[186:187], off
	s_waitcnt vmcnt(8)
	s_waitcnt lgkmcnt(0)
	s_setprio 1
	s_barrier
	v_mfma_f32_16x16x32_bf16 v[150:153], v[90:93], v[162:165], v[150:153]
	v_mfma_f32_16x16x32_bf16 v[150:153], v[102:105], v[166:169], v[150:153]
	v_mfma_f32_16x16x32_bf16 v[146:149], v[114:117], v[162:165], v[146:149]
	v_mfma_f32_16x16x32_bf16 v[146:149], v[126:129], v[166:169], v[146:149]
	v_mfma_f32_16x16x32_bf16 v[118:121], v[114:117], v[170:173], v[118:121]
	v_mfma_f32_16x16x32_bf16 v[118:121], v[126:129], v[174:177], v[118:121]
	v_mfma_f32_16x16x32_bf16 v[122:125], v[90:93], v[170:173], v[122:125]
	v_mfma_f32_16x16x32_bf16 v[122:125], v[102:105], v[174:177], v[122:125]
	v_mfma_f32_16x16x32_bf16 v[98:101], v[90:93], v[178:181], v[98:101]
	v_mfma_f32_16x16x32_bf16 v[98:101], v[102:105], v[182:185], v[98:101]
	v_mfma_f32_16x16x32_bf16 v[94:97], v[114:117], v[178:181], v[94:97]
	v_mfma_f32_16x16x32_bf16 v[94:97], v[126:129], v[182:185], v[94:97]
	v_mfma_f32_16x16x32_bf16 v[74:77], v[114:117], v[204:207], v[74:77]
	v_mfma_f32_16x16x32_bf16 v[74:77], v[126:129], v[208:211], v[74:77]
	v_mfma_f32_16x16x32_bf16 v[78:81], v[90:93], v[204:207], v[78:81]
	v_mfma_f32_16x16x32_bf16 v[78:81], v[102:105], v[208:211], v[78:81]
	v_mfma_f32_16x16x32_bf16 v[134:137], v[138:141], v[162:165], v[134:137]
	v_mfma_f32_16x16x32_bf16 v[134:137], v[142:145], v[166:169], v[134:137]
	v_mfma_f32_16x16x32_bf16 v[130:133], v[154:157], v[162:165], v[130:133]
	v_mfma_f32_16x16x32_bf16 v[130:133], v[158:161], v[166:169], v[130:133]
	v_mfma_f32_16x16x32_bf16 v[106:109], v[154:157], v[170:173], v[106:109]
	v_mfma_f32_16x16x32_bf16 v[106:109], v[158:161], v[174:177], v[106:109]
	v_mfma_f32_16x16x32_bf16 v[110:113], v[138:141], v[170:173], v[110:113]
	v_mfma_f32_16x16x32_bf16 v[110:113], v[142:145], v[174:177], v[110:113]
	v_mfma_f32_16x16x32_bf16 v[86:89], v[138:141], v[178:181], v[86:89]
	v_mfma_f32_16x16x32_bf16 v[86:89], v[142:145], v[182:185], v[86:89]
	v_mfma_f32_16x16x32_bf16 v[82:85], v[154:157], v[178:181], v[82:85]
	v_mfma_f32_16x16x32_bf16 v[82:85], v[158:161], v[182:185], v[82:85]
	v_mfma_f32_16x16x32_bf16 v[66:69], v[154:157], v[204:207], v[66:69]
	v_mfma_f32_16x16x32_bf16 v[66:69], v[158:161], v[208:211], v[66:69]
	v_mfma_f32_16x16x32_bf16 v[70:73], v[138:141], v[204:207], v[70:73]
	v_mfma_f32_16x16x32_bf16 v[70:73], v[142:145], v[208:211], v[70:73]
	s_setprio 0
	s_barrier
	s_add_i32 s22, s50, s2
	v_lshl_add_u64 v[186:187], s[26:27], 0, v[0:1]
	s_mov_b32 m0, s22
	ds_read_b128 v[162:165], v249 offset:16384
	ds_read_b128 v[166:169], v249 offset:17408
	ds_read_b128 v[170:173], v249 offset:18432
	ds_read_b128 v[174:177], v249 offset:19456
	ds_read_b128 v[178:181], v249 offset:20480
	ds_read_b128 v[182:185], v249 offset:21504
	ds_read_b128 v[204:207], v249 offset:22528
	ds_read_b128 v[208:211], v249 offset:23552
	global_load_lds_dwordx4 v[186:187], off
	s_add_i32 m0, s22, 0x2000
	s_add_u32 s22, s26, 0x160000
	v_lshl_add_u64 v[188:189], s[26:27], 0, v[194:195]
	s_addc_u32 s23, s27, 0
	s_add_i32 s50, s51, s2
	global_load_lds_dwordx4 v[188:189], off
	v_lshl_add_u64 v[190:191], s[22:23], 0, v[0:1]
	s_mov_b32 m0, s50
	v_lshl_add_u64 v[192:193], s[28:29], 0, v[196:197]
	global_load_lds_dwordx4 v[190:191], off
	v_lshl_add_u64 v[190:191], s[22:23], 0, v[194:195]
	s_add_i32 m0, s50, 0x2000
	s_nop 0
	global_load_lds_dwordx4 v[190:191], off
	v_lshl_add_u64 v[190:191], s[28:29], 0, v[198:199]
	s_mov_b32 m0, s6
	s_nop 0
	global_load_lds_dwordx4 v[190:191], off
	s_mov_b32 m0, s7
	s_nop 0
	global_load_lds_dwordx4 v[192:193], off
	s_waitcnt vmcnt(8)
	s_waitcnt lgkmcnt(0)
	s_setprio 1
	s_barrier
; #define PG8_STAGE(bufoff, gbase, voff) do { _Pragma("unroll") for (int _i = 0; _i < 2; ++_i) \
;         __builtin_amdgcn_global_load_lds((const unsigned*)((const char*)(gbase) + (voff)[_i]), (LAS unsigned*)(lds + (bufoff) + ldsw + _i * 8192), 16, 0, 0); } while (0)
; #define PG8_LDA(dst, b, h) do { _Pragma("unroll") for (int m = 0; m < 4; ++m) _Pragma("unroll") for (int k = 0; k < 2; ++k) dst[m][k] = *(const LAS bf16x8*)(lds + PG8_SA(b, h) + aoff + m * 2048 + k * 1024); } while (0)
; #define PG8_LDB(dst, b, h) do { _Pragma("unroll") for (int n = 0; n < 2; ++n) _Pragma("unroll") for (int k = 0; k < 2; ++k) dst[n][k] = *(const LAS bf16x8*)(lds + PG8_SB(b, h) + boff + n * 2048 + k * 1024); } while (0)
; #define PG8_MMA(ai, bj, At, Bt) do { __builtin_amdgcn_s_setprio(1); _Pragma("unroll") for (int m = 0; m < 4; ++m) _Pragma("unroll") for (int n = 0; n < 2; ++n) _Pragma("unroll") for (int k = 0; k < 2; ++k) \
;         acc[ai][bj][m][n] = __builtin_amdgcn_mfma_f32_16x16x32_bf16(Bt[n][k], At[m][k], acc[ai][bj][m][n], 0, 0, 0); __builtin_amdgcn_s_setprio(0); } while (0)
; #define PG8_WAIT_V(n) asm volatile("s_waitcnt vmcnt(" #n ")" ::: "memory")
; #define PG8_WAIT_L(n) asm volatile("s_waitcnt lgkmcnt(" #n ")" ::: "memory")
; #define PG8_BAR __builtin_amdgcn_s_barrier()
; #define PG8_SCHED __builtin_amdgcn_sched_barrier(0)
; template <class Epi, class Sched, bool ALIGN_EPI = false, bool SP2 = false>
; __device__ __forceinline__ void gemm_phase(LAS unsigned char* lds, const Gemm g, const Sched& S, const Epi& E) {
;     ...
;             PG8_WAIT_V(8); PG8_WAIT_L(0); PG8_BAR; PG8_MMA(1, 0, At, B0); PG8_MMA(1, 1, At, B1); PG8_BAR; PG8_SCHED;
;             PG8_LDB(B0, 1, 0); PG8_LDB(B1, 1, 1); PG8_SCHED; PG8_LDA(At, 1, 0); PG8_STAGE(PG8_SA(0, 1), a2 + hstep, voffA);
;             PG8_WAIT_V(8); PG8_WAIT_L(0); PG8_BAR; PG8_MMA(0, 0, At, B0); PG8_MMA(0, 1, At, B1); PG8_BAR; PG8_SCHED;
	v_mfma_f32_16x16x32_bf16 v[62:65], v[90:93], v[162:165], v[62:65]
	v_mfma_f32_16x16x32_bf16 v[62:65], v[102:105], v[166:169], v[62:65]
	v_mfma_f32_16x16x32_bf16 v[58:61], v[114:117], v[162:165], v[58:61]
	v_mfma_f32_16x16x32_bf16 v[58:61], v[126:129], v[166:169], v[58:61]
	v_mfma_f32_16x16x32_bf16 v[42:45], v[114:117], v[170:173], v[42:45]
	v_mfma_f32_16x16x32_bf16 v[42:45], v[126:129], v[174:177], v[42:45]
	v_mfma_f32_16x16x32_bf16 v[46:49], v[90:93], v[170:173], v[46:49]
	v_mfma_f32_16x16x32_bf16 v[46:49], v[102:105], v[174:177], v[46:49]
	v_mfma_f32_16x16x32_bf16 v[30:33], v[90:93], v[178:181], v[30:33]
	v_mfma_f32_16x16x32_bf16 v[30:33], v[102:105], v[182:185], v[30:33]
	v_mfma_f32_16x16x32_bf16 v[26:29], v[114:117], v[178:181], v[26:29]
	v_mfma_f32_16x16x32_bf16 v[26:29], v[126:129], v[182:185], v[26:29]
	v_mfma_f32_16x16x32_bf16 v[10:13], v[114:117], v[204:207], v[10:13]
	v_mfma_f32_16x16x32_bf16 v[10:13], v[126:129], v[208:211], v[10:13]
	v_mfma_f32_16x16x32_bf16 v[14:17], v[90:93], v[204:207], v[14:17]
	v_mfma_f32_16x16x32_bf16 v[14:17], v[102:105], v[208:211], v[14:17]
	v_mfma_f32_16x16x32_bf16 v[54:57], v[138:141], v[162:165], v[54:57]
	v_mfma_f32_16x16x32_bf16 v[54:57], v[142:145], v[166:169], v[54:57]
	v_mfma_f32_16x16x32_bf16 v[50:53], v[154:157], v[162:165], v[50:53]
	v_mfma_f32_16x16x32_bf16 v[50:53], v[158:161], v[166:169], v[50:53]
	v_mfma_f32_16x16x32_bf16 v[34:37], v[154:157], v[170:173], v[34:37]
	v_mfma_f32_16x16x32_bf16 v[34:37], v[158:161], v[174:177], v[34:37]
	v_mfma_f32_16x16x32_bf16 v[38:41], v[138:141], v[170:173], v[38:41]
	v_mfma_f32_16x16x32_bf16 v[38:41], v[142:145], v[174:177], v[38:41]
	v_mfma_f32_16x16x32_bf16 v[22:25], v[138:141], v[178:181], v[22:25]
	v_mfma_f32_16x16x32_bf16 v[22:25], v[142:145], v[182:185], v[22:25]
	v_mfma_f32_16x16x32_bf16 v[18:21], v[154:157], v[178:181], v[18:21]
	v_mfma_f32_16x16x32_bf16 v[18:21], v[158:161], v[182:185], v[18:21]
	v_mfma_f32_16x16x32_bf16 v[2:5], v[154:157], v[204:207], v[2:5]
	v_mfma_f32_16x16x32_bf16 v[2:5], v[158:161], v[208:211], v[2:5]
	v_mfma_f32_16x16x32_bf16 v[6:9], v[138:141], v[204:207], v[6:9]
	v_mfma_f32_16x16x32_bf16 v[6:9], v[142:145], v[208:211], v[6:9]
	s_setprio 0
	s_barrier
	s_add_i32 s50, 0, 0x18000
	s_add_i32 s51, 0, 0x1c000
	v_add_u32_e32 v126, s50, v247
	v_add_u32_e32 v158, s51, v247
	ds_read_b128 v[90:93], v126
	ds_read_b128 v[102:105], v126 offset:1024
	ds_read_b128 v[114:117], v126 offset:2048
	ds_read_b128 v[126:129], v126 offset:3072
	ds_read_b128 v[138:141], v158
	ds_read_b128 v[142:145], v158 offset:1024
	ds_read_b128 v[154:157], v158 offset:2048
	ds_read_b128 v[158:161], v158 offset:3072
	s_add_u32 s22, s28, 0x160000
	s_addc_u32 s23, s29, 0
	s_mov_b32 m0, s8
	v_lshl_add_u64 v[212:213], s[22:23], 0, v[198:199]
	ds_read_b128 v[162:165], v249 offset:32768
	ds_read_b128 v[166:169], v249 offset:33792
	ds_read_b128 v[170:173], v249 offset:34816
	ds_read_b128 v[174:177], v249 offset:35840
	ds_read_b128 v[178:181], v249 offset:36864
	ds_read_b128 v[182:185], v249 offset:37888
	ds_read_b128 v[204:207], v249 offset:38912
	ds_read_b128 v[208:211], v249 offset:39936
	global_load_lds_dwordx4 v[212:213], off
	v_lshl_add_u64 v[212:213], s[22:23], 0, v[196:197]
	s_mov_b32 m0, s31
	s_nop 0
	global_load_lds_dwordx4 v[212:213], off
	s_waitcnt vmcnt(8)
	s_waitcnt lgkmcnt(0)
	s_setprio 1
	s_barrier
	v_mfma_f32_16x16x32_bf16 v[150:153], v[90:93], v[162:165], v[150:153]
	v_mfma_f32_16x16x32_bf16 v[150:153], v[102:105], v[166:169], v[150:153]
	v_mfma_f32_16x16x32_bf16 v[146:149], v[114:117], v[162:165], v[146:149]
	v_mfma_f32_16x16x32_bf16 v[146:149], v[126:129], v[166:169], v[146:149]
	v_mfma_f32_16x16x32_bf16 v[118:121], v[114:117], v[170:173], v[118:121]
	v_mfma_f32_16x16x32_bf16 v[118:121], v[126:129], v[174:177], v[118:121]
	v_mfma_f32_16x16x32_bf16 v[122:125], v[90:93], v[170:173], v[122:125]
	v_mfma_f32_16x16x32_bf16 v[122:125], v[102:105], v[174:177], v[122:125]
	v_mfma_f32_16x16x32_bf16 v[98:101], v[90:93], v[178:181], v[98:101]
	v_mfma_f32_16x16x32_bf16 v[98:101], v[102:105], v[182:185], v[98:101]
	v_mfma_f32_16x16x32_bf16 v[94:97], v[114:117], v[178:181], v[94:97]
	v_mfma_f32_16x16x32_bf16 v[94:97], v[126:129], v[182:185], v[94:97]
	v_mfma_f32_16x16x32_bf16 v[74:77], v[114:117], v[204:207], v[74:77]
	v_mfma_f32_16x16x32_bf16 v[74:77], v[126:129], v[208:211], v[74:77]
	v_mfma_f32_16x16x32_bf16 v[78:81], v[90:93], v[204:207], v[78:81]
	v_mfma_f32_16x16x32_bf16 v[78:81], v[102:105], v[208:211], v[78:81]
	v_mfma_f32_16x16x32_bf16 v[134:137], v[138:141], v[162:165], v[134:137]
	v_mfma_f32_16x16x32_bf16 v[134:137], v[142:145], v[166:169], v[134:137]
	v_mfma_f32_16x16x32_bf16 v[130:133], v[154:157], v[162:165], v[130:133]
	v_mfma_f32_16x16x32_bf16 v[130:133], v[158:161], v[166:169], v[130:133]
	v_mfma_f32_16x16x32_bf16 v[106:109], v[154:157], v[170:173], v[106:109]
	v_mfma_f32_16x16x32_bf16 v[106:109], v[158:161], v[174:177], v[106:109]
	v_mfma_f32_16x16x32_bf16 v[110:113], v[138:141], v[170:173], v[110:113]
	v_mfma_f32_16x16x32_bf16 v[110:113], v[142:145], v[174:177], v[110:113]
	v_mfma_f32_16x16x32_bf16 v[86:89], v[138:141], v[178:181], v[86:89]
	v_mfma_f32_16x16x32_bf16 v[86:89], v[142:145], v[182:185], v[86:89]
	v_mfma_f32_16x16x32_bf16 v[82:85], v[154:157], v[178:181], v[82:85]
	v_mfma_f32_16x16x32_bf16 v[82:85], v[158:161], v[182:185], v[82:85]
	v_mfma_f32_16x16x32_bf16 v[66:69], v[154:157], v[204:207], v[66:69]
	v_mfma_f32_16x16x32_bf16 v[66:69], v[158:161], v[208:211], v[66:69]
	v_mfma_f32_16x16x32_bf16 v[70:73], v[138:141], v[204:207], v[70:73]
	v_mfma_f32_16x16x32_bf16 v[70:73], v[142:145], v[208:211], v[70:73]
	s_setprio 0
	s_barrier
; #define PG8_STAGE(bufoff, gbase, voff) do { _Pragma("unroll") for (int _i = 0; _i < 2; ++_i) \
;         __builtin_amdgcn_global_load_lds((const unsigned*)((const char*)(gbase) + (voff)[_i]), (LAS unsigned*)(lds + (bufoff) + ldsw + _i * 8192), 16, 0, 0); } while (0)
; #define PG8_LDA(dst, b, h) do { _Pragma("unroll") for (int m = 0; m < 4; ++m) _Pragma("unroll") for (int k = 0; k < 2; ++k) dst[m][k] = *(const LAS bf16x8*)(lds + PG8_SA(b, h) + aoff + m * 2048 + k * 1024); } while (0)
; #define PG8_MMA(ai, bj, At, Bt) do { __builtin_amdgcn_s_setprio(1); _Pragma("unroll") for (int m = 0; m < 4; ++m) _Pragma("unroll") for (int n = 0; n < 2; ++n) _Pragma("unroll") for (int k = 0; k < 2; ++k) \
;         acc[ai][bj][m][n] = __builtin_amdgcn_mfma_f32_16x16x32_bf16(Bt[n][k], At[m][k], acc[ai][bj][m][n], 0, 0, 0); __builtin_amdgcn_s_setprio(0); } while (0)
; #define PG8_WAIT_V(n) asm volatile("s_waitcnt vmcnt(" #n ")" ::: "memory")
; #define PG8_WAIT_L(n) asm volatile("s_waitcnt lgkmcnt(" #n ")" ::: "memory")
; #define PG8_BAR __builtin_amdgcn_s_barrier()
; #define PG8_SCHED __builtin_amdgcn_sched_barrier(0)
; template <class Epi, class Sched, bool ALIGN_EPI = false, bool SP2 = false>
; __device__ __forceinline__ void gemm_phase(LAS unsigned char* lds, const Gemm g, const Sched& S, const Epi& E) {
;     ...
;             PG8_WAIT_V(8); PG8_WAIT_L(0); PG8_BAR; PG8_MMA(0, 0, At, B0); PG8_MMA(0, 1, At, B1); PG8_BAR; PG8_SCHED;
;             PG8_LDA(At, 1, 1); PG8_STAGE(PG8_SB(1, 0), b3, voffB); PG8_STAGE(PG8_SB(1, 1), b3 + hstep, voffB); PG8_STAGE(PG8_SA(1, 0), a3, voffA);
;             PG8_WAIT_V(8); PG8_WAIT_L(0); PG8_BAR; PG8_MMA(1, 0, At, B0); PG8_MMA(1, 1, At, B1); PG8_BAR; PG8_SCHED;
;     ...
;         if constexpr (ALIGN_EPI) { if (wr == 0) PG8_BAR; }
	s_add_i32 s22, s50, s2
	v_lshl_add_u64 v[186:187], v[186:187], 0, s[12:13]
	s_mov_b32 m0, s22
	ds_read_b128 v[162:165], v249 offset:49152
	ds_read_b128 v[166:169], v249 offset:50176
	ds_read_b128 v[170:173], v249 offset:51200
	ds_read_b128 v[174:177], v249 offset:52224
	ds_read_b128 v[178:181], v249 offset:53248
	ds_read_b128 v[182:185], v249 offset:54272
	ds_read_b128 v[204:207], v249 offset:55296
	ds_read_b128 v[208:211], v249 offset:56320
	global_load_lds_dwordx4 v[186:187], off
	s_add_i32 m0, s22, 0x2000
	s_add_u32 s22, s26, 0x160080
	v_lshl_add_u64 v[186:187], v[188:189], 0, s[12:13]
	s_addc_u32 s23, s27, 0
	s_add_i32 s26, s51, s2
	global_load_lds_dwordx4 v[186:187], off
	v_lshl_add_u64 v[186:187], s[22:23], 0, v[0:1]
	s_mov_b32 m0, s26
	s_nop 0
	global_load_lds_dwordx4 v[186:187], off
	v_lshl_add_u64 v[186:187], s[22:23], 0, v[194:195]
	s_add_i32 m0, s26, 0x2000
	s_nop 0
	global_load_lds_dwordx4 v[186:187], off
	v_lshl_add_u64 v[186:187], v[190:191], 0, s[12:13]
	s_mov_b32 m0, s35
	s_nop 0
	global_load_lds_dwordx4 v[186:187], off
	v_lshl_add_u64 v[186:187], v[192:193], 0, s[12:13]
	s_mov_b32 m0, s40
	s_nop 0
	global_load_lds_dwordx4 v[186:187], off
	s_waitcnt vmcnt(8)
	s_waitcnt lgkmcnt(0)
	s_setprio 1
	s_barrier
	v_mfma_f32_16x16x32_bf16 v[62:65], v[90:93], v[162:165], v[62:65]
	v_mfma_f32_16x16x32_bf16 v[62:65], v[102:105], v[166:169], v[62:65]
	v_mfma_f32_16x16x32_bf16 v[58:61], v[114:117], v[162:165], v[58:61]
	v_mfma_f32_16x16x32_bf16 v[58:61], v[126:129], v[166:169], v[58:61]
	v_mfma_f32_16x16x32_bf16 v[42:45], v[114:117], v[170:173], v[42:45]
	v_mfma_f32_16x16x32_bf16 v[42:45], v[126:129], v[174:177], v[42:45]
	v_mfma_f32_16x16x32_bf16 v[46:49], v[90:93], v[170:173], v[46:49]
	v_mfma_f32_16x16x32_bf16 v[46:49], v[102:105], v[174:177], v[46:49]
	v_mfma_f32_16x16x32_bf16 v[30:33], v[90:93], v[178:181], v[30:33]
	v_mfma_f32_16x16x32_bf16 v[30:33], v[102:105], v[182:185], v[30:33]
	v_mfma_f32_16x16x32_bf16 v[26:29], v[114:117], v[178:181], v[26:29]
	v_mfma_f32_16x16x32_bf16 v[26:29], v[126:129], v[182:185], v[26:29]
	v_mfma_f32_16x16x32_bf16 v[10:13], v[114:117], v[204:207], v[10:13]
	v_mfma_f32_16x16x32_bf16 v[10:13], v[126:129], v[208:211], v[10:13]
	v_mfma_f32_16x16x32_bf16 v[14:17], v[90:93], v[204:207], v[14:17]
	v_mfma_f32_16x16x32_bf16 v[14:17], v[102:105], v[208:211], v[14:17]
	v_mfma_f32_16x16x32_bf16 v[54:57], v[138:141], v[162:165], v[54:57]
	v_mfma_f32_16x16x32_bf16 v[54:57], v[142:145], v[166:169], v[54:57]
	v_mfma_f32_16x16x32_bf16 v[50:53], v[154:157], v[162:165], v[50:53]
	v_mfma_f32_16x16x32_bf16 v[50:53], v[158:161], v[166:169], v[50:53]
	v_mfma_f32_16x16x32_bf16 v[34:37], v[154:157], v[170:173], v[34:37]
	v_mfma_f32_16x16x32_bf16 v[34:37], v[158:161], v[174:177], v[34:37]
	v_mfma_f32_16x16x32_bf16 v[38:41], v[138:141], v[170:173], v[38:41]
	v_mfma_f32_16x16x32_bf16 v[38:41], v[142:145], v[174:177], v[38:41]
	v_mfma_f32_16x16x32_bf16 v[22:25], v[138:141], v[178:181], v[22:25]
	v_mfma_f32_16x16x32_bf16 v[22:25], v[142:145], v[182:185], v[22:25]
	v_mfma_f32_16x16x32_bf16 v[18:21], v[154:157], v[178:181], v[18:21]
	v_mfma_f32_16x16x32_bf16 v[18:21], v[158:161], v[182:185], v[18:21]
	v_mfma_f32_16x16x32_bf16 v[2:5], v[154:157], v[204:207], v[2:5]
	v_mfma_f32_16x16x32_bf16 v[2:5], v[158:161], v[208:211], v[2:5]
	v_mfma_f32_16x16x32_bf16 v[6:9], v[138:141], v[204:207], v[6:9]
	v_mfma_f32_16x16x32_bf16 v[6:9], v[142:145], v[208:211], v[6:9]
	s_setprio 0
	s_barrier
	s_add_i32 s49, s49, 2
	s_add_u32 s47, s47, 0x100
	s_addc_u32 s48, s48, 0
	s_cmpk_gt_u32 s49, 0x55
	s_mov_b64 s[22:23], s[24:25]
	s_cbranch_scc0 .LBB0_257
	s_and_b64 vcc, exec, s[18:19]
	s_cbranch_vccz .LBB0_260
	s_barrier

; #define PG8_STAGE(bufoff, gbase, voff) do { _Pragma("unroll") for (int _i = 0; _i < 2; ++_i) \
;         __builtin_amdgcn_global_load_lds((const unsigned*)((const char*)(gbase) + (voff)[_i]), (LAS unsigned*)(lds + (bufoff) + ldsw + _i * 8192), 16, 0, 0); } while (0)
; #define PG8_LDA(dst, b, h) do { _Pragma("unroll") for (int m = 0; m < 4; ++m) _Pragma("unroll") for (int k = 0; k < 2; ++k) dst[m][k] = *(const LAS bf16x8*)(lds + PG8_SA(b, h) + aoff + m * 2048 + k * 1024); } while (0)
; #define PG8_LDB(dst, b, h) do { _Pragma("unroll") for (int n = 0; n < 2; ++n) _Pragma("unroll") for (int k = 0; k < 2; ++k) dst[n][k] = *(const LAS bf16x8*)(lds + PG8_SB(b, h) + boff + n * 2048 + k * 1024); } while (0)
; #define PG8_MMA(ai, bj, At, Bt) do { __builtin_amdgcn_s_setprio(1); _Pragma("unroll") for (int m = 0; m < 4; ++m) _Pragma("unroll") for (int n = 0; n < 2; ++n) _Pragma("unroll") for (int k = 0; k < 2; ++k) \
;         acc[ai][bj][m][n] = __builtin_amdgcn_mfma_f32_16x16x32_bf16(Bt[n][k], At[m][k], acc[ai][bj][m][n], 0, 0, 0); __builtin_amdgcn_s_setprio(0); } while (0)
; #define PG8_WAIT_V(n) asm volatile("s_waitcnt vmcnt(" #n ")" ::: "memory")
; #define PG8_WAIT_L(n) asm volatile("s_waitcnt lgkmcnt(" #n ")" ::: "memory")
; #define PG8_BAR __builtin_amdgcn_s_barrier()
; #define PG8_SCHED __builtin_amdgcn_sched_barrier(0)
; template <class Epi, class Sched, bool ALIGN_EPI = false, bool SP2 = false>
; __device__ __forceinline__ void gemm_phase(LAS unsigned char* lds, const Gemm g, const Sched& S, const Epi& E) {
;     ...
;             const bool last = (t == nt - 2);
;             const char* a1 = cA + (size_t)(t + 1) * kstep;
;             const char* a2 = last ? nA : cA + (size_t)(t + 2) * kstep; const char* b2 = last ? nB : cB + (size_t)(t + 2) * kstep;
;             const char* a3 = a2 + kstep; const char* b3 = b2 + kstep;
;             if (last && has_next) S.a_ready(nxt);
;             if constexpr (SP2) {
;             PG8_LDB(B0, 0, 0); PG8_LDB(B1, 0, 1); PG8_SCHED; PG8_LDA(At, 0, 0); PG8_STAGE(PG8_SA(1, 1), a1 + hstep, voffA);
;             PG8_WAIT_V(8); PG8_WAIT_L(0); PG8_BAR; PG8_MMA(0, 0, At, B0); PG8_MMA(0, 1, At, B1); PG8_BAR; PG8_SCHED;
;             PG8_LDA(At, 0, 1); PG8_STAGE(PG8_SB(0, 0), b2, voffB); PG8_STAGE(PG8_SB(0, 1), b2 + hstep, voffB); PG8_STAGE(PG8_SA(0, 0), a2, voffA);
.LBB0_359:
	s_add_u32 s28, s26, 0xfff80080
	s_addc_u32 s29, s27, -1
	s_add_i32 s41, 0, 0x10000
	s_cmp_eq_u32 s40, 28
	s_cselect_b32 s31, s6, s29
	s_cselect_b32 s30, s7, s28
	v_add_u32_e32 v0, s41, v159
	s_cselect_b32 s29, s8, s35
	s_cselect_b32 s28, s19, s21
	s_add_i32 s57, 0, 0x14000
	ds_read_b128 v[142:145], v0
	ds_read_b128 v[146:149], v0 offset:1024
	ds_read_b128 v[150:153], v0 offset:2048
	ds_read_b128 v[154:157], v0 offset:3072
	v_add_u32_e32 v0, s57, v159
	ds_read_b128 v[162:165], v0
	ds_read_b128 v[166:169], v0 offset:1024
	ds_read_b128 v[170:173], v0 offset:2048
	ds_read_b128 v[174:177], v0 offset:3072
	v_lshl_add_u64 v[210:211], s[26:27], 0, v[138:139]
	s_add_i32 m0, s44, 0xc000
	ds_read_b128 v[178:181], v161
	ds_read_b128 v[182:185], v161 offset:1024
	ds_read_b128 v[186:189], v161 offset:2048
	ds_read_b128 v[190:193], v161 offset:3072
	ds_read_b128 v[194:197], v161 offset:4096
	ds_read_b128 v[198:201], v161 offset:5120
	ds_read_b128 v[202:205], v161 offset:6144
	ds_read_b128 v[206:209], v161 offset:7168
	global_load_lds_dwordx4 v[210:211], off
	v_lshl_add_u64 v[210:211], s[26:27], 0, v[140:141]
	s_add_i32 m0, s44, 0xe000
	s_nop 0
	global_load_lds_dwordx4 v[210:211], off
	s_waitcnt vmcnt(8)
	s_waitcnt lgkmcnt(0)
	s_setprio 1
	s_barrier
	v_mfma_f32_16x16x32_bf16 v[126:129], v[142:145], v[178:181], v[126:129]
	v_mfma_f32_16x16x32_bf16 v[126:129], v[146:149], v[182:185], v[126:129]
	v_mfma_f32_16x16x32_bf16 v[122:125], v[150:153], v[178:181], v[122:125]
	v_mfma_f32_16x16x32_bf16 v[122:125], v[154:157], v[182:185], v[122:125]
	v_mfma_f32_16x16x32_bf16 v[106:109], v[150:153], v[186:189], v[106:109]
	v_mfma_f32_16x16x32_bf16 v[106:109], v[154:157], v[190:193], v[106:109]
	v_mfma_f32_16x16x32_bf16 v[110:113], v[142:145], v[186:189], v[110:113]
	v_mfma_f32_16x16x32_bf16 v[110:113], v[146:149], v[190:193], v[110:113]
	v_mfma_f32_16x16x32_bf16 v[94:97], v[142:145], v[194:197], v[94:97]
	v_mfma_f32_16x16x32_bf16 v[94:97], v[146:149], v[198:201], v[94:97]
	v_mfma_f32_16x16x32_bf16 v[90:93], v[150:153], v[194:197], v[90:93]
	v_mfma_f32_16x16x32_bf16 v[90:93], v[154:157], v[198:201], v[90:93]
	v_mfma_f32_16x16x32_bf16 v[74:77], v[150:153], v[202:205], v[74:77]
	v_mfma_f32_16x16x32_bf16 v[74:77], v[154:157], v[206:209], v[74:77]
	v_mfma_f32_16x16x32_bf16 v[78:81], v[142:145], v[202:205], v[78:81]
	v_mfma_f32_16x16x32_bf16 v[78:81], v[146:149], v[206:209], v[78:81]
	v_mfma_f32_16x16x32_bf16 v[118:121], v[162:165], v[178:181], v[118:121]
	v_mfma_f32_16x16x32_bf16 v[118:121], v[166:169], v[182:185], v[118:121]
	v_mfma_f32_16x16x32_bf16 v[114:117], v[170:173], v[178:181], v[114:117]
	v_mfma_f32_16x16x32_bf16 v[114:117], v[174:177], v[182:185], v[114:117]
	v_mfma_f32_16x16x32_bf16 v[98:101], v[170:173], v[186:189], v[98:101]
	v_mfma_f32_16x16x32_bf16 v[98:101], v[174:177], v[190:193], v[98:101]
	v_mfma_f32_16x16x32_bf16 v[102:105], v[162:165], v[186:189], v[102:105]
	v_mfma_f32_16x16x32_bf16 v[102:105], v[166:169], v[190:193], v[102:105]
	v_mfma_f32_16x16x32_bf16 v[86:89], v[162:165], v[194:197], v[86:89]
	v_mfma_f32_16x16x32_bf16 v[86:89], v[166:169], v[198:201], v[86:89]
	v_mfma_f32_16x16x32_bf16 v[82:85], v[170:173], v[194:197], v[82:85]
	v_mfma_f32_16x16x32_bf16 v[82:85], v[174:177], v[198:201], v[82:85]
	v_mfma_f32_16x16x32_bf16 v[66:69], v[170:173], v[202:205], v[66:69]
	v_mfma_f32_16x16x32_bf16 v[66:69], v[174:177], v[206:209], v[66:69]
	v_mfma_f32_16x16x32_bf16 v[70:73], v[162:165], v[202:205], v[70:73]
	v_mfma_f32_16x16x32_bf16 v[70:73], v[166:169], v[206:209], v[70:73]
	s_setprio 0
	s_barrier
	s_add_i32 s41, s41, s9
	v_lshl_add_u64 v[210:211], s[28:29], 0, v[134:135]
	s_mov_b32 m0, s41
	ds_read_b128 v[178:181], v161 offset:16384
	ds_read_b128 v[182:185], v161 offset:17408
	ds_read_b128 v[186:189], v161 offset:18432
	ds_read_b128 v[190:193], v161 offset:19456
	ds_read_b128 v[194:197], v161 offset:20480
	ds_read_b128 v[198:201], v161 offset:21504
	ds_read_b128 v[202:205], v161 offset:22528
	ds_read_b128 v[206:209], v161 offset:23552
	global_load_lds_dwordx4 v[210:211], off
	s_add_i32 m0, s41, 0x2000
	s_add_u32 s58, s28, 0x80000
	v_lshl_add_u64 v[212:213], s[28:29], 0, v[130:131]
	s_addc_u32 s59, s29, 0
	s_add_i32 s41, s57, s9
	global_load_lds_dwordx4 v[212:213], off
	v_lshl_add_u64 v[214:215], s[58:59], 0, v[134:135]
	s_mov_b32 m0, s41
	v_lshl_add_u64 v[216:217], s[30:31], 0, v[132:133]
	global_load_lds_dwordx4 v[214:215], off
	v_lshl_add_u64 v[214:215], s[58:59], 0, v[130:131]
	s_add_i32 m0, s41, 0x2000
	s_nop 0
	global_load_lds_dwordx4 v[214:215], off
	v_lshl_add_u64 v[214:215], s[30:31], 0, v[136:137]
	s_mov_b32 m0, s44
	s_nop 0
	global_load_lds_dwordx4 v[214:215], off
	s_mov_b32 m0, s45
	s_nop 0
	global_load_lds_dwordx4 v[216:217], off
	s_waitcnt vmcnt(8)
	s_waitcnt lgkmcnt(0)
	s_setprio 1
	s_barrier
; #define PG8_STAGE(bufoff, gbase, voff) do { _Pragma("unroll") for (int _i = 0; _i < 2; ++_i) \
;         __builtin_amdgcn_global_load_lds((const unsigned*)((const char*)(gbase) + (voff)[_i]), (LAS unsigned*)(lds + (bufoff) + ldsw + _i * 8192), 16, 0, 0); } while (0)
; #define PG8_LDA(dst, b, h) do { _Pragma("unroll") for (int m = 0; m < 4; ++m) _Pragma("unroll") for (int k = 0; k < 2; ++k) dst[m][k] = *(const LAS bf16x8*)(lds + PG8_SA(b, h) + aoff + m * 2048 + k * 1024); } while (0)
; #define PG8_LDB(dst, b, h) do { _Pragma("unroll") for (int n = 0; n < 2; ++n) _Pragma("unroll") for (int k = 0; k < 2; ++k) dst[n][k] = *(const LAS bf16x8*)(lds + PG8_SB(b, h) + boff + n * 2048 + k * 1024); } while (0)
; #define PG8_MMA(ai, bj, At, Bt) do { __builtin_amdgcn_s_setprio(1); _Pragma("unroll") for (int m = 0; m < 4; ++m) _Pragma("unroll") for (int n = 0; n < 2; ++n) _Pragma("unroll") for (int k = 0; k < 2; ++k) \
;         acc[ai][bj][m][n] = __builtin_amdgcn_mfma_f32_16x16x32_bf16(Bt[n][k], At[m][k], acc[ai][bj][m][n], 0, 0, 0); __builtin_amdgcn_s_setprio(0); } while (0)
; #define PG8_WAIT_V(n) asm volatile("s_waitcnt vmcnt(" #n ")" ::: "memory")
; #define PG8_WAIT_L(n) asm volatile("s_waitcnt lgkmcnt(" #n ")" ::: "memory")
; #define PG8_BAR __builtin_amdgcn_s_barrier()
; #define PG8_SCHED __builtin_amdgcn_sched_barrier(0)
; template <class Epi, class Sched, bool ALIGN_EPI = false, bool SP2 = false>
; __device__ __forceinline__ void gemm_phase(LAS unsigned char* lds, const Gemm g, const Sched& S, const Epi& E) {
;     ...
;             PG8_WAIT_V(8); PG8_WAIT_L(0); PG8_BAR; PG8_MMA(1, 0, At, B0); PG8_MMA(1, 1, At, B1); PG8_BAR; PG8_SCHED;
;             PG8_LDB(B0, 1, 0); PG8_LDB(B1, 1, 1); PG8_SCHED; PG8_LDA(At, 1, 0); PG8_STAGE(PG8_SA(0, 1), a2 + hstep, voffA);
;             PG8_WAIT_V(8); PG8_WAIT_L(0); PG8_BAR; PG8_MMA(0, 0, At, B0); PG8_MMA(0, 1, At, B1); PG8_BAR; PG8_SCHED;
	v_mfma_f32_16x16x32_bf16 v[62:65], v[142:145], v[178:181], v[62:65]
	v_mfma_f32_16x16x32_bf16 v[62:65], v[146:149], v[182:185], v[62:65]
	v_mfma_f32_16x16x32_bf16 v[58:61], v[150:153], v[178:181], v[58:61]
	v_mfma_f32_16x16x32_bf16 v[58:61], v[154:157], v[182:185], v[58:61]
	v_mfma_f32_16x16x32_bf16 v[42:45], v[150:153], v[186:189], v[42:45]
	v_mfma_f32_16x16x32_bf16 v[42:45], v[154:157], v[190:193], v[42:45]
	v_mfma_f32_16x16x32_bf16 v[46:49], v[142:145], v[186:189], v[46:49]
	v_mfma_f32_16x16x32_bf16 v[46:49], v[146:149], v[190:193], v[46:49]
	v_mfma_f32_16x16x32_bf16 v[30:33], v[142:145], v[194:197], v[30:33]
	v_mfma_f32_16x16x32_bf16 v[30:33], v[146:149], v[198:201], v[30:33]
	v_mfma_f32_16x16x32_bf16 v[26:29], v[150:153], v[194:197], v[26:29]
	v_mfma_f32_16x16x32_bf16 v[26:29], v[154:157], v[198:201], v[26:29]
	v_mfma_f32_16x16x32_bf16 v[10:13], v[150:153], v[202:205], v[10:13]
	v_mfma_f32_16x16x32_bf16 v[10:13], v[154:157], v[206:209], v[10:13]
	v_mfma_f32_16x16x32_bf16 v[14:17], v[142:145], v[202:205], v[14:17]
	v_mfma_f32_16x16x32_bf16 v[14:17], v[146:149], v[206:209], v[14:17]
	v_mfma_f32_16x16x32_bf16 v[54:57], v[162:165], v[178:181], v[54:57]
	v_mfma_f32_16x16x32_bf16 v[54:57], v[166:169], v[182:185], v[54:57]
	v_mfma_f32_16x16x32_bf16 v[50:53], v[170:173], v[178:181], v[50:53]
	v_mfma_f32_16x16x32_bf16 v[50:53], v[174:177], v[182:185], v[50:53]
	v_mfma_f32_16x16x32_bf16 v[34:37], v[170:173], v[186:189], v[34:37]
	v_mfma_f32_16x16x32_bf16 v[34:37], v[174:177], v[190:193], v[34:37]
	v_mfma_f32_16x16x32_bf16 v[38:41], v[162:165], v[186:189], v[38:41]
	v_mfma_f32_16x16x32_bf16 v[38:41], v[166:169], v[190:193], v[38:41]
	v_mfma_f32_16x16x32_bf16 v[22:25], v[162:165], v[194:197], v[22:25]
	v_mfma_f32_16x16x32_bf16 v[22:25], v[166:169], v[198:201], v[22:25]
	v_mfma_f32_16x16x32_bf16 v[18:21], v[170:173], v[194:197], v[18:21]
	v_mfma_f32_16x16x32_bf16 v[18:21], v[174:177], v[198:201], v[18:21]
	v_mfma_f32_16x16x32_bf16 v[2:5], v[170:173], v[202:205], v[2:5]
	v_mfma_f32_16x16x32_bf16 v[2:5], v[174:177], v[206:209], v[2:5]
	v_mfma_f32_16x16x32_bf16 v[6:9], v[162:165], v[202:205], v[6:9]
	v_mfma_f32_16x16x32_bf16 v[6:9], v[166:169], v[206:209], v[6:9]
	s_setprio 0
	s_barrier
	s_add_i32 s41, 0, 0x18000
	v_add_u32_e32 v0, s41, v159
	s_add_i32 s57, 0, 0x1c000
	ds_read_b128 v[142:145], v0
	ds_read_b128 v[146:149], v0 offset:1024
	ds_read_b128 v[150:153], v0 offset:2048
	ds_read_b128 v[154:157], v0 offset:3072
	v_add_u32_e32 v0, s57, v159
	ds_read_b128 v[162:165], v0
	ds_read_b128 v[166:169], v0 offset:1024
	ds_read_b128 v[170:173], v0 offset:2048
	ds_read_b128 v[174:177], v0 offset:3072
	s_add_u32 s30, s30, 0x80000
	s_addc_u32 s31, s31, 0
	s_mov_b32 m0, s47
	v_lshl_add_u64 v[218:219], s[30:31], 0, v[136:137]
	ds_read_b128 v[178:181], v161 offset:32768
	ds_read_b128 v[182:185], v161 offset:33792
	ds_read_b128 v[186:189], v161 offset:34816
	ds_read_b128 v[190:193], v161 offset:35840
	ds_read_b128 v[194:197], v161 offset:36864
	ds_read_b128 v[198:201], v161 offset:37888
	ds_read_b128 v[202:205], v161 offset:38912
	ds_read_b128 v[206:209], v161 offset:39936
	global_load_lds_dwordx4 v[218:219], off
	v_lshl_add_u64 v[218:219], s[30:31], 0, v[132:133]
	s_mov_b32 m0, s48
	s_nop 0
	global_load_lds_dwordx4 v[218:219], off
	s_waitcnt vmcnt(8)
	s_waitcnt lgkmcnt(0)
	s_setprio 1
	s_barrier
	v_mfma_f32_16x16x32_bf16 v[126:129], v[142:145], v[178:181], v[126:129]
	v_mfma_f32_16x16x32_bf16 v[126:129], v[146:149], v[182:185], v[126:129]
	v_mfma_f32_16x16x32_bf16 v[122:125], v[150:153], v[178:181], v[122:125]
	v_mfma_f32_16x16x32_bf16 v[122:125], v[154:157], v[182:185], v[122:125]
	v_mfma_f32_16x16x32_bf16 v[106:109], v[150:153], v[186:189], v[106:109]
	v_mfma_f32_16x16x32_bf16 v[106:109], v[154:157], v[190:193], v[106:109]
	v_mfma_f32_16x16x32_bf16 v[110:113], v[142:145], v[186:189], v[110:113]
	v_mfma_f32_16x16x32_bf16 v[110:113], v[146:149], v[190:193], v[110:113]
	v_mfma_f32_16x16x32_bf16 v[94:97], v[142:145], v[194:197], v[94:97]
	v_mfma_f32_16x16x32_bf16 v[94:97], v[146:149], v[198:201], v[94:97]
	v_mfma_f32_16x16x32_bf16 v[90:93], v[150:153], v[194:197], v[90:93]
	v_mfma_f32_16x16x32_bf16 v[90:93], v[154:157], v[198:201], v[90:93]
	v_mfma_f32_16x16x32_bf16 v[74:77], v[150:153], v[202:205], v[74:77]
	v_mfma_f32_16x16x32_bf16 v[74:77], v[154:157], v[206:209], v[74:77]
	v_mfma_f32_16x16x32_bf16 v[78:81], v[142:145], v[202:205], v[78:81]
	v_mfma_f32_16x16x32_bf16 v[78:81], v[146:149], v[206:209], v[78:81]
	v_mfma_f32_16x16x32_bf16 v[118:121], v[162:165], v[178:181], v[118:121]
	v_mfma_f32_16x16x32_bf16 v[118:121], v[166:169], v[182:185], v[118:121]
	v_mfma_f32_16x16x32_bf16 v[114:117], v[170:173], v[178:181], v[114:117]
	v_mfma_f32_16x16x32_bf16 v[114:117], v[174:177], v[182:185], v[114:117]
	v_mfma_f32_16x16x32_bf16 v[98:101], v[170:173], v[186:189], v[98:101]
	v_mfma_f32_16x16x32_bf16 v[98:101], v[174:177], v[190:193], v[98:101]
	v_mfma_f32_16x16x32_bf16 v[102:105], v[162:165], v[186:189], v[102:105]
	v_mfma_f32_16x16x32_bf16 v[102:105], v[166:169], v[190:193], v[102:105]
	v_mfma_f32_16x16x32_bf16 v[86:89], v[162:165], v[194:197], v[86:89]
	v_mfma_f32_16x16x32_bf16 v[86:89], v[166:169], v[198:201], v[86:89]
	v_mfma_f32_16x16x32_bf16 v[82:85], v[170:173], v[194:197], v[82:85]
	v_mfma_f32_16x16x32_bf16 v[82:85], v[174:177], v[198:201], v[82:85]
	v_mfma_f32_16x16x32_bf16 v[66:69], v[170:173], v[202:205], v[66:69]
	v_mfma_f32_16x16x32_bf16 v[66:69], v[174:177], v[206:209], v[66:69]
	v_mfma_f32_16x16x32_bf16 v[70:73], v[162:165], v[202:205], v[70:73]
	v_mfma_f32_16x16x32_bf16 v[70:73], v[166:169], v[206:209], v[70:73]
	s_setprio 0
	s_barrier
; #define PG8_STAGE(bufoff, gbase, voff) do { _Pragma("unroll") for (int _i = 0; _i < 2; ++_i) \
;         __builtin_amdgcn_global_load_lds((const unsigned*)((const char*)(gbase) + (voff)[_i]), (LAS unsigned*)(lds + (bufoff) + ldsw + _i * 8192), 16, 0, 0); } while (0)
; #define PG8_LDA(dst, b, h) do { _Pragma("unroll") for (int m = 0; m < 4; ++m) _Pragma("unroll") for (int k = 0; k < 2; ++k) dst[m][k] = *(const LAS bf16x8*)(lds + PG8_SA(b, h) + aoff + m * 2048 + k * 1024); } while (0)
; #define PG8_MMA(ai, bj, At, Bt) do { __builtin_amdgcn_s_setprio(1); _Pragma("unroll") for (int m = 0; m < 4; ++m) _Pragma("unroll") for (int n = 0; n < 2; ++n) _Pragma("unroll") for (int k = 0; k < 2; ++k) \
;         acc[ai][bj][m][n] = __builtin_amdgcn_mfma_f32_16x16x32_bf16(Bt[n][k], At[m][k], acc[ai][bj][m][n], 0, 0, 0); __builtin_amdgcn_s_setprio(0); } while (0)
; #define PG8_WAIT_V(n) asm volatile("s_waitcnt vmcnt(" #n ")" ::: "memory")
; #define PG8_WAIT_L(n) asm volatile("s_waitcnt lgkmcnt(" #n ")" ::: "memory")
; #define PG8_BAR __builtin_amdgcn_s_barrier()
; #define PG8_SCHED __builtin_amdgcn_sched_barrier(0)
; template <class Epi, class Sched, bool ALIGN_EPI = false, bool SP2 = false>
; __device__ __forceinline__ void gemm_phase(LAS unsigned char* lds, const Gemm g, const Sched& S, const Epi& E) {
;     ...
;             PG8_WAIT_V(8); PG8_WAIT_L(0); PG8_BAR; PG8_MMA(0, 0, At, B0); PG8_MMA(0, 1, At, B1); PG8_BAR; PG8_SCHED;
;             PG8_LDA(At, 1, 1); PG8_STAGE(PG8_SB(1, 0), b3, voffB); PG8_STAGE(PG8_SB(1, 1), b3 + hstep, voffB); PG8_STAGE(PG8_SA(1, 0), a3, voffA);
;             PG8_WAIT_V(8); PG8_WAIT_L(0); PG8_BAR; PG8_MMA(1, 0, At, B0); PG8_MMA(1, 1, At, B1); PG8_BAR; PG8_SCHED;
;     ...
;         if constexpr (ALIGN_EPI) { if (wr == 0) PG8_BAR; }
	s_add_i32 s30, s41, s9
	v_lshl_add_u64 v[210:211], v[210:211], 0, s[12:13]
	s_mov_b32 m0, s30
	ds_read_b128 v[178:181], v161 offset:49152
	ds_read_b128 v[182:185], v161 offset:50176
	ds_read_b128 v[186:189], v161 offset:51200
	ds_read_b128 v[190:193], v161 offset:52224
	ds_read_b128 v[194:197], v161 offset:53248
	ds_read_b128 v[198:201], v161 offset:54272
	ds_read_b128 v[202:205], v161 offset:55296
	ds_read_b128 v[206:209], v161 offset:56320
	global_load_lds_dwordx4 v[210:211], off
	s_add_i32 m0, s30, 0x2000
	s_add_u32 s28, s28, 0x80080
	v_lshl_add_u64 v[210:211], v[212:213], 0, s[12:13]
	s_addc_u32 s29, s29, 0
	s_add_i32 s30, s57, s9
	global_load_lds_dwordx4 v[210:211], off
	v_lshl_add_u64 v[210:211], s[28:29], 0, v[134:135]
	s_mov_b32 m0, s30
	s_nop 0
	global_load_lds_dwordx4 v[210:211], off
	v_lshl_add_u64 v[210:211], s[28:29], 0, v[130:131]
	s_add_i32 m0, s30, 0x2000
	s_nop 0
	global_load_lds_dwordx4 v[210:211], off
	v_lshl_add_u64 v[210:211], v[214:215], 0, s[12:13]
	s_mov_b32 m0, s53
	s_nop 0
	global_load_lds_dwordx4 v[210:211], off
	v_lshl_add_u64 v[210:211], v[216:217], 0, s[12:13]
	s_mov_b32 m0, s54
	s_nop 0
	global_load_lds_dwordx4 v[210:211], off
	s_waitcnt vmcnt(8)
	s_waitcnt lgkmcnt(0)
	s_setprio 1
	s_barrier
	v_mfma_f32_16x16x32_bf16 v[62:65], v[142:145], v[178:181], v[62:65]
	v_mfma_f32_16x16x32_bf16 v[62:65], v[146:149], v[182:185], v[62:65]
	v_mfma_f32_16x16x32_bf16 v[58:61], v[150:153], v[178:181], v[58:61]
	v_mfma_f32_16x16x32_bf16 v[58:61], v[154:157], v[182:185], v[58:61]
	v_mfma_f32_16x16x32_bf16 v[42:45], v[150:153], v[186:189], v[42:45]
	v_mfma_f32_16x16x32_bf16 v[42:45], v[154:157], v[190:193], v[42:45]
	v_mfma_f32_16x16x32_bf16 v[46:49], v[142:145], v[186:189], v[46:49]
	v_mfma_f32_16x16x32_bf16 v[46:49], v[146:149], v[190:193], v[46:49]
	v_mfma_f32_16x16x32_bf16 v[30:33], v[142:145], v[194:197], v[30:33]
	v_mfma_f32_16x16x32_bf16 v[30:33], v[146:149], v[198:201], v[30:33]
	v_mfma_f32_16x16x32_bf16 v[26:29], v[150:153], v[194:197], v[26:29]
	v_mfma_f32_16x16x32_bf16 v[26:29], v[154:157], v[198:201], v[26:29]
	v_mfma_f32_16x16x32_bf16 v[10:13], v[150:153], v[202:205], v[10:13]
	v_mfma_f32_16x16x32_bf16 v[10:13], v[154:157], v[206:209], v[10:13]
	v_mfma_f32_16x16x32_bf16 v[14:17], v[142:145], v[202:205], v[14:17]
	v_mfma_f32_16x16x32_bf16 v[14:17], v[146:149], v[206:209], v[14:17]
	v_mfma_f32_16x16x32_bf16 v[54:57], v[162:165], v[178:181], v[54:57]
	v_mfma_f32_16x16x32_bf16 v[54:57], v[166:169], v[182:185], v[54:57]
	v_mfma_f32_16x16x32_bf16 v[50:53], v[170:173], v[178:181], v[50:53]
	v_mfma_f32_16x16x32_bf16 v[50:53], v[174:177], v[182:185], v[50:53]
	v_mfma_f32_16x16x32_bf16 v[34:37], v[170:173], v[186:189], v[34:37]
	v_mfma_f32_16x16x32_bf16 v[34:37], v[174:177], v[190:193], v[34:37]
	v_mfma_f32_16x16x32_bf16 v[38:41], v[162:165], v[186:189], v[38:41]
	v_mfma_f32_16x16x32_bf16 v[38:41], v[166:169], v[190:193], v[38:41]
	v_mfma_f32_16x16x32_bf16 v[22:25], v[162:165], v[194:197], v[22:25]
	v_mfma_f32_16x16x32_bf16 v[22:25], v[166:169], v[198:201], v[22:25]
	v_mfma_f32_16x16x32_bf16 v[18:21], v[170:173], v[194:197], v[18:21]
	v_mfma_f32_16x16x32_bf16 v[18:21], v[174:177], v[198:201], v[18:21]
	v_mfma_f32_16x16x32_bf16 v[2:5], v[170:173], v[202:205], v[2:5]
	v_mfma_f32_16x16x32_bf16 v[2:5], v[174:177], v[206:209], v[2:5]
	v_mfma_f32_16x16x32_bf16 v[6:9], v[162:165], v[202:205], v[6:9]
	v_mfma_f32_16x16x32_bf16 v[6:9], v[166:169], v[206:209], v[6:9]
	s_setprio 0
	s_barrier
	s_add_i32 s40, s40, 2
	s_add_u32 s26, s26, 0x100
	s_addc_u32 s27, s27, 0
	s_add_u32 s21, s21, 0x100
	s_addc_u32 s35, s35, 0
	s_cmp_gt_u32 s40, 29
	s_cbranch_scc0 .LBB0_359
	s_and_b64 vcc, exec, s[16:17]
	s_cbranch_vccz .LBB0_362
	s_barrier

; #define PG8_STAGE(bufoff, gbase, voff) do { _Pragma("unroll") for (int _i = 0; _i < 2; ++_i) \
;         __builtin_amdgcn_global_load_lds((const unsigned*)((const char*)(gbase) + (voff)[_i]), (LAS unsigned*)(lds + (bufoff) + ldsw + _i * 8192), 16, 0, 0); } while (0)
; #define PG8_LDA(dst, b, h) do { _Pragma("unroll") for (int m = 0; m < 4; ++m) _Pragma("unroll") for (int k = 0; k < 2; ++k) dst[m][k] = *(const LAS bf16x8*)(lds + PG8_SA(b, h) + aoff + m * 2048 + k * 1024); } while (0)
; #define PG8_LDB(dst, b, h) do { _Pragma("unroll") for (int n = 0; n < 2; ++n) _Pragma("unroll") for (int k = 0; k < 2; ++k) dst[n][k] = *(const LAS bf16x8*)(lds + PG8_SB(b, h) + boff + n * 2048 + k * 1024); } while (0)
; #define PG8_MMA(ai, bj, At, Bt) do { __builtin_amdgcn_s_setprio(1); _Pragma("unroll") for (int m = 0; m < 4; ++m) _Pragma("unroll") for (int n = 0; n < 2; ++n) _Pragma("unroll") for (int k = 0; k < 2; ++k) \
;         acc[ai][bj][m][n] = __builtin_amdgcn_mfma_f32_16x16x32_bf16(Bt[n][k], At[m][k], acc[ai][bj][m][n], 0, 0, 0); __builtin_amdgcn_s_setprio(0); } while (0)
; #define PG8_WAIT_V(n) asm volatile("s_waitcnt vmcnt(" #n ")" ::: "memory")
; #define PG8_WAIT_L(n) asm volatile("s_waitcnt lgkmcnt(" #n ")" ::: "memory")
; #define PG8_BAR __builtin_amdgcn_s_barrier()
; #define PG8_SCHED __builtin_amdgcn_sched_barrier(0)
; template <class Epi, class Sched, bool ALIGN_EPI = false, bool SP2 = false>
; __device__ __forceinline__ void gemm_phase(LAS unsigned char* lds, const Gemm g, const Sched& S, const Epi& E) {
;     ...
;             const bool last = (t == nt - 2);
;             const char* a1 = cA + (size_t)(t + 1) * kstep;
;             const char* a2 = last ? nA : cA + (size_t)(t + 2) * kstep; const char* b2 = last ? nB : cB + (size_t)(t + 2) * kstep;
;             const char* a3 = a2 + kstep; const char* b3 = b2 + kstep;
;             if (last && has_next) S.a_ready(nxt);
;             if constexpr (SP2) {
;             PG8_LDB(B0, 0, 0); PG8_LDB(B1, 0, 1); PG8_SCHED; PG8_LDA(At, 0, 0); PG8_STAGE(PG8_SA(1, 1), a1 + hstep, voffA);
;             PG8_WAIT_V(8); PG8_WAIT_L(0); PG8_BAR; PG8_MMA(0, 0, At, B0); PG8_MMA(0, 1, At, B1); PG8_BAR; PG8_SCHED;
;             PG8_LDA(At, 0, 1); PG8_STAGE(PG8_SB(0, 0), b2, voffB); PG8_STAGE(PG8_SB(0, 1), b2 + hstep, voffB); PG8_STAGE(PG8_SA(0, 0), a2, voffA);
.LBB0_833:
	s_add_u32 s28, s26, 0xfff80080
	s_addc_u32 s29, s27, -1
	s_add_i32 s53, 0, 0x10000
	s_cmp_eq_u32 s52, 28
	s_cselect_b32 s31, s21, s29
	s_cselect_b32 s30, s48, s28
	s_cselect_b32 s29, s19, s51
	s_cselect_b32 s28, s49, s50
	s_add_i32 s56, 0, 0x14000
	v_add_u32_e32 v134, s53, v247
	v_add_u32_e32 v158, s56, v247
	ds_read_b128 v[106:109], v134
	ds_read_b128 v[110:113], v134 offset:1024
	ds_read_b128 v[122:125], v134 offset:2048
	ds_read_b128 v[134:137], v134 offset:3072
	ds_read_b128 v[146:149], v158
	ds_read_b128 v[150:153], v158 offset:1024
	ds_read_b128 v[154:157], v158 offset:2048
	ds_read_b128 v[158:161], v158 offset:3072
	v_lshl_add_u64 v[204:205], s[26:27], 0, v[200:201]
	s_add_i32 m0, s8, 0xc000
	ds_read_b128 v[162:165], v249
	ds_read_b128 v[166:169], v249 offset:1024
	ds_read_b128 v[170:173], v249 offset:2048
	ds_read_b128 v[174:177], v249 offset:3072
	ds_read_b128 v[178:181], v249 offset:4096
	ds_read_b128 v[182:185], v249 offset:5120
	ds_read_b128 v[186:189], v249 offset:6144
	ds_read_b128 v[190:193], v249 offset:7168
	global_load_lds_dwordx4 v[204:205], off
	v_lshl_add_u64 v[204:205], s[26:27], 0, v[202:203]
	s_add_i32 m0, s8, 0xe000
	s_nop 0
	global_load_lds_dwordx4 v[204:205], off
	s_waitcnt vmcnt(8)
	s_waitcnt lgkmcnt(0)
	s_setprio 1
	s_barrier
	v_mfma_f32_16x16x32_bf16 v[142:145], v[106:109], v[162:165], v[142:145]
	v_mfma_f32_16x16x32_bf16 v[142:145], v[110:113], v[166:169], v[142:145]
	v_mfma_f32_16x16x32_bf16 v[138:141], v[122:125], v[162:165], v[138:141]
	v_mfma_f32_16x16x32_bf16 v[138:141], v[134:137], v[166:169], v[138:141]
	v_mfma_f32_16x16x32_bf16 v[114:117], v[122:125], v[170:173], v[114:117]
	v_mfma_f32_16x16x32_bf16 v[114:117], v[134:137], v[174:177], v[114:117]
	v_mfma_f32_16x16x32_bf16 v[118:121], v[106:109], v[170:173], v[118:121]
	v_mfma_f32_16x16x32_bf16 v[118:121], v[110:113], v[174:177], v[118:121]
	v_mfma_f32_16x16x32_bf16 v[94:97], v[106:109], v[178:181], v[94:97]
	v_mfma_f32_16x16x32_bf16 v[94:97], v[110:113], v[182:185], v[94:97]
	v_mfma_f32_16x16x32_bf16 v[90:93], v[122:125], v[178:181], v[90:93]
	v_mfma_f32_16x16x32_bf16 v[90:93], v[134:137], v[182:185], v[90:93]
	v_mfma_f32_16x16x32_bf16 v[74:77], v[122:125], v[186:189], v[74:77]
	v_mfma_f32_16x16x32_bf16 v[74:77], v[134:137], v[190:193], v[74:77]
	v_mfma_f32_16x16x32_bf16 v[78:81], v[106:109], v[186:189], v[78:81]
	v_mfma_f32_16x16x32_bf16 v[78:81], v[110:113], v[190:193], v[78:81]
	v_mfma_f32_16x16x32_bf16 v[130:133], v[146:149], v[162:165], v[130:133]
	v_mfma_f32_16x16x32_bf16 v[130:133], v[150:153], v[166:169], v[130:133]
	v_mfma_f32_16x16x32_bf16 v[126:129], v[154:157], v[162:165], v[126:129]
	v_mfma_f32_16x16x32_bf16 v[126:129], v[158:161], v[166:169], v[126:129]
	v_mfma_f32_16x16x32_bf16 v[98:101], v[154:157], v[170:173], v[98:101]
	v_mfma_f32_16x16x32_bf16 v[98:101], v[158:161], v[174:177], v[98:101]
	v_mfma_f32_16x16x32_bf16 v[102:105], v[146:149], v[170:173], v[102:105]
	v_mfma_f32_16x16x32_bf16 v[102:105], v[150:153], v[174:177], v[102:105]
	v_mfma_f32_16x16x32_bf16 v[86:89], v[146:149], v[178:181], v[86:89]
	v_mfma_f32_16x16x32_bf16 v[86:89], v[150:153], v[182:185], v[86:89]
	v_mfma_f32_16x16x32_bf16 v[82:85], v[154:157], v[178:181], v[82:85]
	v_mfma_f32_16x16x32_bf16 v[82:85], v[158:161], v[182:185], v[82:85]
	v_mfma_f32_16x16x32_bf16 v[66:69], v[154:157], v[186:189], v[66:69]
	v_mfma_f32_16x16x32_bf16 v[66:69], v[158:161], v[190:193], v[66:69]
	v_mfma_f32_16x16x32_bf16 v[70:73], v[146:149], v[186:189], v[70:73]
	v_mfma_f32_16x16x32_bf16 v[70:73], v[150:153], v[190:193], v[70:73]
	s_setprio 0
	s_barrier
	s_add_i32 s53, s53, s7
	v_lshl_add_u64 v[204:205], s[28:29], 0, v[0:1]
	s_mov_b32 m0, s53
	ds_read_b128 v[162:165], v249 offset:16384
	ds_read_b128 v[166:169], v249 offset:17408
	ds_read_b128 v[170:173], v249 offset:18432
	ds_read_b128 v[174:177], v249 offset:19456
	ds_read_b128 v[178:181], v249 offset:20480
	ds_read_b128 v[182:185], v249 offset:21504
	ds_read_b128 v[186:189], v249 offset:22528
	ds_read_b128 v[190:193], v249 offset:23552
	global_load_lds_dwordx4 v[204:205], off
	s_add_i32 m0, s53, 0x2000
	s_add_u32 s54, s28, 0x80000
	v_lshl_add_u64 v[206:207], s[28:29], 0, v[194:195]
	s_addc_u32 s55, s29, 0
	s_add_i32 s53, s56, s7
	global_load_lds_dwordx4 v[206:207], off
	v_lshl_add_u64 v[208:209], s[54:55], 0, v[0:1]
	s_mov_b32 m0, s53
	v_lshl_add_u64 v[210:211], s[30:31], 0, v[196:197]
	global_load_lds_dwordx4 v[208:209], off
	v_lshl_add_u64 v[208:209], s[54:55], 0, v[194:195]
	s_add_i32 m0, s53, 0x2000
	s_nop 0
	global_load_lds_dwordx4 v[208:209], off
	v_lshl_add_u64 v[208:209], s[30:31], 0, v[198:199]
	s_mov_b32 m0, s8
	s_nop 0
	global_load_lds_dwordx4 v[208:209], off
	s_mov_b32 m0, s9
	s_nop 0
	global_load_lds_dwordx4 v[210:211], off
	s_waitcnt vmcnt(8)
	s_waitcnt lgkmcnt(0)
	s_setprio 1
	s_barrier
; #define PG8_STAGE(bufoff, gbase, voff) do { _Pragma("unroll") for (int _i = 0; _i < 2; ++_i) \
;         __builtin_amdgcn_global_load_lds((const unsigned*)((const char*)(gbase) + (voff)[_i]), (LAS unsigned*)(lds + (bufoff) + ldsw + _i * 8192), 16, 0, 0); } while (0)
; #define PG8_LDA(dst, b, h) do { _Pragma("unroll") for (int m = 0; m < 4; ++m) _Pragma("unroll") for (int k = 0; k < 2; ++k) dst[m][k] = *(const LAS bf16x8*)(lds + PG8_SA(b, h) + aoff + m * 2048 + k * 1024); } while (0)
; #define PG8_LDB(dst, b, h) do { _Pragma("unroll") for (int n = 0; n < 2; ++n) _Pragma("unroll") for (int k = 0; k < 2; ++k) dst[n][k] = *(const LAS bf16x8*)(lds + PG8_SB(b, h) + boff + n * 2048 + k * 1024); } while (0)
; #define PG8_MMA(ai, bj, At, Bt) do { __builtin_amdgcn_s_setprio(1); _Pragma("unroll") for (int m = 0; m < 4; ++m) _Pragma("unroll") for (int n = 0; n < 2; ++n) _Pragma("unroll") for (int k = 0; k < 2; ++k) \
;         acc[ai][bj][m][n] = __builtin_amdgcn_mfma_f32_16x16x32_bf16(Bt[n][k], At[m][k], acc[ai][bj][m][n], 0, 0, 0); __builtin_amdgcn_s_setprio(0); } while (0)
; #define PG8_WAIT_V(n) asm volatile("s_waitcnt vmcnt(" #n ")" ::: "memory")
; #define PG8_WAIT_L(n) asm volatile("s_waitcnt lgkmcnt(" #n ")" ::: "memory")
; #define PG8_BAR __builtin_amdgcn_s_barrier()
; #define PG8_SCHED __builtin_amdgcn_sched_barrier(0)
; template <class Epi, class Sched, bool ALIGN_EPI = false, bool SP2 = false>
; __device__ __forceinline__ void gemm_phase(LAS unsigned char* lds, const Gemm g, const Sched& S, const Epi& E) {
;     ...
;             PG8_WAIT_V(8); PG8_WAIT_L(0); PG8_BAR; PG8_MMA(1, 0, At, B0); PG8_MMA(1, 1, At, B1); PG8_BAR; PG8_SCHED;
;             PG8_LDB(B0, 1, 0); PG8_LDB(B1, 1, 1); PG8_SCHED; PG8_LDA(At, 1, 0); PG8_STAGE(PG8_SA(0, 1), a2 + hstep, voffA);
;             PG8_WAIT_V(8); PG8_WAIT_L(0); PG8_BAR; PG8_MMA(0, 0, At, B0); PG8_MMA(0, 1, At, B1); PG8_BAR; PG8_SCHED;
	v_mfma_f32_16x16x32_bf16 v[62:65], v[106:109], v[162:165], v[62:65]
	v_mfma_f32_16x16x32_bf16 v[62:65], v[110:113], v[166:169], v[62:65]
	v_mfma_f32_16x16x32_bf16 v[58:61], v[122:125], v[162:165], v[58:61]
	v_mfma_f32_16x16x32_bf16 v[58:61], v[134:137], v[166:169], v[58:61]
	v_mfma_f32_16x16x32_bf16 v[42:45], v[122:125], v[170:173], v[42:45]
	v_mfma_f32_16x16x32_bf16 v[42:45], v[134:137], v[174:177], v[42:45]
	v_mfma_f32_16x16x32_bf16 v[46:49], v[106:109], v[170:173], v[46:49]
	v_mfma_f32_16x16x32_bf16 v[46:49], v[110:113], v[174:177], v[46:49]
	v_mfma_f32_16x16x32_bf16 v[30:33], v[106:109], v[178:181], v[30:33]
	v_mfma_f32_16x16x32_bf16 v[30:33], v[110:113], v[182:185], v[30:33]
	v_mfma_f32_16x16x32_bf16 v[26:29], v[122:125], v[178:181], v[26:29]
	v_mfma_f32_16x16x32_bf16 v[26:29], v[134:137], v[182:185], v[26:29]
	v_mfma_f32_16x16x32_bf16 v[10:13], v[122:125], v[186:189], v[10:13]
	v_mfma_f32_16x16x32_bf16 v[10:13], v[134:137], v[190:193], v[10:13]
	v_mfma_f32_16x16x32_bf16 v[14:17], v[106:109], v[186:189], v[14:17]
	v_mfma_f32_16x16x32_bf16 v[14:17], v[110:113], v[190:193], v[14:17]
	v_mfma_f32_16x16x32_bf16 v[54:57], v[146:149], v[162:165], v[54:57]
	v_mfma_f32_16x16x32_bf16 v[54:57], v[150:153], v[166:169], v[54:57]
	v_mfma_f32_16x16x32_bf16 v[50:53], v[154:157], v[162:165], v[50:53]
	v_mfma_f32_16x16x32_bf16 v[50:53], v[158:161], v[166:169], v[50:53]
	v_mfma_f32_16x16x32_bf16 v[34:37], v[154:157], v[170:173], v[34:37]
	v_mfma_f32_16x16x32_bf16 v[34:37], v[158:161], v[174:177], v[34:37]
	v_mfma_f32_16x16x32_bf16 v[38:41], v[146:149], v[170:173], v[38:41]
	v_mfma_f32_16x16x32_bf16 v[38:41], v[150:153], v[174:177], v[38:41]
	v_mfma_f32_16x16x32_bf16 v[22:25], v[146:149], v[178:181], v[22:25]
	v_mfma_f32_16x16x32_bf16 v[22:25], v[150:153], v[182:185], v[22:25]
	v_mfma_f32_16x16x32_bf16 v[18:21], v[154:157], v[178:181], v[18:21]
	v_mfma_f32_16x16x32_bf16 v[18:21], v[158:161], v[182:185], v[18:21]
	v_mfma_f32_16x16x32_bf16 v[2:5], v[154:157], v[186:189], v[2:5]
	v_mfma_f32_16x16x32_bf16 v[2:5], v[158:161], v[190:193], v[2:5]
	v_mfma_f32_16x16x32_bf16 v[6:9], v[146:149], v[186:189], v[6:9]
	v_mfma_f32_16x16x32_bf16 v[6:9], v[150:153], v[190:193], v[6:9]
	s_setprio 0
	s_barrier
	s_add_i32 s53, 0, 0x18000
	s_add_i32 s54, 0, 0x1c000
	v_add_u32_e32 v134, s53, v247
	v_add_u32_e32 v158, s54, v247
	ds_read_b128 v[106:109], v134
	ds_read_b128 v[110:113], v134 offset:1024
	ds_read_b128 v[122:125], v134 offset:2048
	ds_read_b128 v[134:137], v134 offset:3072
	ds_read_b128 v[146:149], v158
	ds_read_b128 v[150:153], v158 offset:1024
	ds_read_b128 v[154:157], v158 offset:2048
	ds_read_b128 v[158:161], v158 offset:3072
	s_add_u32 s30, s30, 0x80000
	s_addc_u32 s31, s31, 0
	s_mov_b32 m0, s35
	v_lshl_add_u64 v[212:213], s[30:31], 0, v[198:199]
	ds_read_b128 v[162:165], v249 offset:32768
	ds_read_b128 v[166:169], v249 offset:33792
	ds_read_b128 v[170:173], v249 offset:34816
	ds_read_b128 v[174:177], v249 offset:35840
	ds_read_b128 v[178:181], v249 offset:36864
	ds_read_b128 v[182:185], v249 offset:37888
	ds_read_b128 v[186:189], v249 offset:38912
	ds_read_b128 v[190:193], v249 offset:39936
	global_load_lds_dwordx4 v[212:213], off
	v_lshl_add_u64 v[212:213], s[30:31], 0, v[196:197]
	s_mov_b32 m0, s42
	s_nop 0
	global_load_lds_dwordx4 v[212:213], off
	s_waitcnt vmcnt(8)
	s_waitcnt lgkmcnt(0)
	s_setprio 1
	s_barrier
	v_mfma_f32_16x16x32_bf16 v[142:145], v[106:109], v[162:165], v[142:145]
	v_mfma_f32_16x16x32_bf16 v[142:145], v[110:113], v[166:169], v[142:145]
	v_mfma_f32_16x16x32_bf16 v[138:141], v[122:125], v[162:165], v[138:141]
	v_mfma_f32_16x16x32_bf16 v[138:141], v[134:137], v[166:169], v[138:141]
	v_mfma_f32_16x16x32_bf16 v[114:117], v[122:125], v[170:173], v[114:117]
	v_mfma_f32_16x16x32_bf16 v[114:117], v[134:137], v[174:177], v[114:117]
	v_mfma_f32_16x16x32_bf16 v[118:121], v[106:109], v[170:173], v[118:121]
	v_mfma_f32_16x16x32_bf16 v[118:121], v[110:113], v[174:177], v[118:121]
	v_mfma_f32_16x16x32_bf16 v[94:97], v[106:109], v[178:181], v[94:97]
	v_mfma_f32_16x16x32_bf16 v[94:97], v[110:113], v[182:185], v[94:97]
	v_mfma_f32_16x16x32_bf16 v[90:93], v[122:125], v[178:181], v[90:93]
	v_mfma_f32_16x16x32_bf16 v[90:93], v[134:137], v[182:185], v[90:93]
	v_mfma_f32_16x16x32_bf16 v[74:77], v[122:125], v[186:189], v[74:77]
	v_mfma_f32_16x16x32_bf16 v[74:77], v[134:137], v[190:193], v[74:77]
	v_mfma_f32_16x16x32_bf16 v[78:81], v[106:109], v[186:189], v[78:81]
	v_mfma_f32_16x16x32_bf16 v[78:81], v[110:113], v[190:193], v[78:81]
	v_mfma_f32_16x16x32_bf16 v[130:133], v[146:149], v[162:165], v[130:133]
	v_mfma_f32_16x16x32_bf16 v[130:133], v[150:153], v[166:169], v[130:133]
	v_mfma_f32_16x16x32_bf16 v[126:129], v[154:157], v[162:165], v[126:129]
	v_mfma_f32_16x16x32_bf16 v[126:129], v[158:161], v[166:169], v[126:129]
	v_mfma_f32_16x16x32_bf16 v[98:101], v[154:157], v[170:173], v[98:101]
	v_mfma_f32_16x16x32_bf16 v[98:101], v[158:161], v[174:177], v[98:101]
	v_mfma_f32_16x16x32_bf16 v[102:105], v[146:149], v[170:173], v[102:105]
	v_mfma_f32_16x16x32_bf16 v[102:105], v[150:153], v[174:177], v[102:105]
	v_mfma_f32_16x16x32_bf16 v[86:89], v[146:149], v[178:181], v[86:89]
	v_mfma_f32_16x16x32_bf16 v[86:89], v[150:153], v[182:185], v[86:89]
	v_mfma_f32_16x16x32_bf16 v[82:85], v[154:157], v[178:181], v[82:85]
	v_mfma_f32_16x16x32_bf16 v[82:85], v[158:161], v[182:185], v[82:85]
	v_mfma_f32_16x16x32_bf16 v[66:69], v[154:157], v[186:189], v[66:69]
	v_mfma_f32_16x16x32_bf16 v[66:69], v[158:161], v[190:193], v[66:69]
	v_mfma_f32_16x16x32_bf16 v[70:73], v[146:149], v[186:189], v[70:73]
	v_mfma_f32_16x16x32_bf16 v[70:73], v[150:153], v[190:193], v[70:73]
	s_setprio 0
	s_barrier
; #define PG8_STAGE(bufoff, gbase, voff) do { _Pragma("unroll") for (int _i = 0; _i < 2; ++_i) \
;         __builtin_amdgcn_global_load_lds((const unsigned*)((const char*)(gbase) + (voff)[_i]), (LAS unsigned*)(lds + (bufoff) + ldsw + _i * 8192), 16, 0, 0); } while (0)
; #define PG8_LDA(dst, b, h) do { _Pragma("unroll") for (int m = 0; m < 4; ++m) _Pragma("unroll") for (int k = 0; k < 2; ++k) dst[m][k] = *(const LAS bf16x8*)(lds + PG8_SA(b, h) + aoff + m * 2048 + k * 1024); } while (0)
; #define PG8_MMA(ai, bj, At, Bt) do { __builtin_amdgcn_s_setprio(1); _Pragma("unroll") for (int m = 0; m < 4; ++m) _Pragma("unroll") for (int n = 0; n < 2; ++n) _Pragma("unroll") for (int k = 0; k < 2; ++k) \
;         acc[ai][bj][m][n] = __builtin_amdgcn_mfma_f32_16x16x32_bf16(Bt[n][k], At[m][k], acc[ai][bj][m][n], 0, 0, 0); __builtin_amdgcn_s_setprio(0); } while (0)
; #define PG8_WAIT_V(n) asm volatile("s_waitcnt vmcnt(" #n ")" ::: "memory")
; #define PG8_WAIT_L(n) asm volatile("s_waitcnt lgkmcnt(" #n ")" ::: "memory")
; #define PG8_BAR __builtin_amdgcn_s_barrier()
; #define PG8_SCHED __builtin_amdgcn_sched_barrier(0)
; template <class Epi, class Sched, bool ALIGN_EPI = false, bool SP2 = false>
; __device__ __forceinline__ void gemm_phase(LAS unsigned char* lds, const Gemm g, const Sched& S, const Epi& E) {
;     ...
;             PG8_WAIT_V(8); PG8_WAIT_L(0); PG8_BAR; PG8_MMA(0, 0, At, B0); PG8_MMA(0, 1, At, B1); PG8_BAR; PG8_SCHED;
;             PG8_LDA(At, 1, 1); PG8_STAGE(PG8_SB(1, 0), b3, voffB); PG8_STAGE(PG8_SB(1, 1), b3 + hstep, voffB); PG8_STAGE(PG8_SA(1, 0), a3, voffA);
;             PG8_WAIT_V(8); PG8_WAIT_L(0); PG8_BAR; PG8_MMA(1, 0, At, B0); PG8_MMA(1, 1, At, B1); PG8_BAR; PG8_SCHED;
;     ...
;         if constexpr (ALIGN_EPI) { if (wr == 0) PG8_BAR; }
	s_add_i32 s30, s53, s7
	v_lshl_add_u64 v[204:205], v[204:205], 0, s[12:13]
	s_mov_b32 m0, s30
	ds_read_b128 v[162:165], v249 offset:49152
	ds_read_b128 v[166:169], v249 offset:50176
	ds_read_b128 v[170:173], v249 offset:51200
	ds_read_b128 v[174:177], v249 offset:52224
	ds_read_b128 v[178:181], v249 offset:53248
	ds_read_b128 v[182:185], v249 offset:54272
	ds_read_b128 v[186:189], v249 offset:55296
	ds_read_b128 v[190:193], v249 offset:56320
	global_load_lds_dwordx4 v[204:205], off
	s_add_i32 m0, s30, 0x2000
	s_add_u32 s28, s28, 0x80080
	v_lshl_add_u64 v[204:205], v[206:207], 0, s[12:13]
	s_addc_u32 s29, s29, 0
	s_add_i32 s30, s54, s7
	global_load_lds_dwordx4 v[204:205], off
	v_lshl_add_u64 v[204:205], s[28:29], 0, v[0:1]
	s_mov_b32 m0, s30
	s_nop 0
	global_load_lds_dwordx4 v[204:205], off
	v_lshl_add_u64 v[204:205], s[28:29], 0, v[194:195]
	s_add_i32 m0, s30, 0x2000
	s_nop 0
	global_load_lds_dwordx4 v[204:205], off
	v_lshl_add_u64 v[204:205], v[208:209], 0, s[12:13]
	s_mov_b32 m0, s43
	s_nop 0
	global_load_lds_dwordx4 v[204:205], off
	v_lshl_add_u64 v[204:205], v[210:211], 0, s[12:13]
	s_mov_b32 m0, s44
	s_nop 0
	global_load_lds_dwordx4 v[204:205], off
	s_waitcnt vmcnt(8)
	s_waitcnt lgkmcnt(0)
	s_setprio 1
	s_barrier
	v_mfma_f32_16x16x32_bf16 v[62:65], v[106:109], v[162:165], v[62:65]
	v_mfma_f32_16x16x32_bf16 v[62:65], v[110:113], v[166:169], v[62:65]
	v_mfma_f32_16x16x32_bf16 v[58:61], v[122:125], v[162:165], v[58:61]
	v_mfma_f32_16x16x32_bf16 v[58:61], v[134:137], v[166:169], v[58:61]
	v_mfma_f32_16x16x32_bf16 v[42:45], v[122:125], v[170:173], v[42:45]
	v_mfma_f32_16x16x32_bf16 v[42:45], v[134:137], v[174:177], v[42:45]
	v_mfma_f32_16x16x32_bf16 v[46:49], v[106:109], v[170:173], v[46:49]
	v_mfma_f32_16x16x32_bf16 v[46:49], v[110:113], v[174:177], v[46:49]
	v_mfma_f32_16x16x32_bf16 v[30:33], v[106:109], v[178:181], v[30:33]
	v_mfma_f32_16x16x32_bf16 v[30:33], v[110:113], v[182:185], v[30:33]
	v_mfma_f32_16x16x32_bf16 v[26:29], v[122:125], v[178:181], v[26:29]
	v_mfma_f32_16x16x32_bf16 v[26:29], v[134:137], v[182:185], v[26:29]
	v_mfma_f32_16x16x32_bf16 v[10:13], v[122:125], v[186:189], v[10:13]
	v_mfma_f32_16x16x32_bf16 v[10:13], v[134:137], v[190:193], v[10:13]
	v_mfma_f32_16x16x32_bf16 v[14:17], v[106:109], v[186:189], v[14:17]
	v_mfma_f32_16x16x32_bf16 v[14:17], v[110:113], v[190:193], v[14:17]
	v_mfma_f32_16x16x32_bf16 v[54:57], v[146:149], v[162:165], v[54:57]
	v_mfma_f32_16x16x32_bf16 v[54:57], v[150:153], v[166:169], v[54:57]
	v_mfma_f32_16x16x32_bf16 v[50:53], v[154:157], v[162:165], v[50:53]
	v_mfma_f32_16x16x32_bf16 v[50:53], v[158:161], v[166:169], v[50:53]
	v_mfma_f32_16x16x32_bf16 v[34:37], v[154:157], v[170:173], v[34:37]
	v_mfma_f32_16x16x32_bf16 v[34:37], v[158:161], v[174:177], v[34:37]
	v_mfma_f32_16x16x32_bf16 v[38:41], v[146:149], v[170:173], v[38:41]
	v_mfma_f32_16x16x32_bf16 v[38:41], v[150:153], v[174:177], v[38:41]
	v_mfma_f32_16x16x32_bf16 v[22:25], v[146:149], v[178:181], v[22:25]
	v_mfma_f32_16x16x32_bf16 v[22:25], v[150:153], v[182:185], v[22:25]
	v_mfma_f32_16x16x32_bf16 v[18:21], v[154:157], v[178:181], v[18:21]
	v_mfma_f32_16x16x32_bf16 v[18:21], v[158:161], v[182:185], v[18:21]
	v_mfma_f32_16x16x32_bf16 v[2:5], v[154:157], v[186:189], v[2:5]
	v_mfma_f32_16x16x32_bf16 v[2:5], v[158:161], v[190:193], v[2:5]
	v_mfma_f32_16x16x32_bf16 v[6:9], v[146:149], v[186:189], v[6:9]
	v_mfma_f32_16x16x32_bf16 v[6:9], v[150:153], v[190:193], v[6:9]
	s_setprio 0
	s_barrier
	s_add_i32 s52, s52, 2
	s_add_u32 s26, s26, 0x100
	s_addc_u32 s27, s27, 0
	s_add_u32 s50, s50, 0x100
	s_addc_u32 s51, s51, 0
	s_cmp_gt_u32 s52, 29
	s_cbranch_scc0 .LBB0_833
	s_and_b64 vcc, exec, s[16:17]
	s_cbranch_vccz .LBB0_836
	s_barrier

; #define PG8_STAGE(bufoff, gbase, voff) do { _Pragma("unroll") for (int _i = 0; _i < 2; ++_i) \
;         __builtin_amdgcn_global_load_lds((const unsigned*)((const char*)(gbase) + (voff)[_i]), (LAS unsigned*)(lds + (bufoff) + ldsw + _i * 8192), 16, 0, 0); } while (0)
; #define PG8_LDA(dst, b, h) do { _Pragma("unroll") for (int m = 0; m < 4; ++m) _Pragma("unroll") for (int k = 0; k < 2; ++k) dst[m][k] = *(const LAS bf16x8*)(lds + PG8_SA(b, h) + aoff + m * 2048 + k * 1024); } while (0)
; #define PG8_LDB(dst, b, h) do { _Pragma("unroll") for (int n = 0; n < 2; ++n) _Pragma("unroll") for (int k = 0; k < 2; ++k) dst[n][k] = *(const LAS bf16x8*)(lds + PG8_SB(b, h) + boff + n * 2048 + k * 1024); } while (0)
; #define PG8_MMA(ai, bj, At, Bt) do { __builtin_amdgcn_s_setprio(1); _Pragma("unroll") for (int m = 0; m < 4; ++m) _Pragma("unroll") for (int n = 0; n < 2; ++n) _Pragma("unroll") for (int k = 0; k < 2; ++k) \
;         acc[ai][bj][m][n] = __builtin_amdgcn_mfma_f32_16x16x32_bf16(Bt[n][k], At[m][k], acc[ai][bj][m][n], 0, 0, 0); __builtin_amdgcn_s_setprio(0); } while (0)
; #define PG8_WAIT_V(n) asm volatile("s_waitcnt vmcnt(" #n ")" ::: "memory")
; #define PG8_WAIT_L(n) asm volatile("s_waitcnt lgkmcnt(" #n ")" ::: "memory")
; #define PG8_BAR __builtin_amdgcn_s_barrier()
; #define PG8_SCHED __builtin_amdgcn_sched_barrier(0)
; template <class Epi, class Sched, bool ALIGN_EPI = false, bool SP2 = false>
; __device__ __forceinline__ void gemm_phase(LAS unsigned char* lds, const Gemm g, const Sched& S, const Epi& E) {
;     ...
;             const bool last = (t == nt - 2);
;             const char* a1 = cA + (size_t)(t + 1) * kstep;
;             const char* a2 = last ? nA : cA + (size_t)(t + 2) * kstep; const char* b2 = last ? nB : cB + (size_t)(t + 2) * kstep;
;             const char* a3 = a2 + kstep; const char* b3 = b2 + kstep;
;             if (last && has_next) S.a_ready(nxt);
;             if constexpr (SP2) {
;             PG8_LDB(B0, 0, 0); PG8_LDB(B1, 0, 1); PG8_SCHED; PG8_LDA(At, 0, 0); PG8_STAGE(PG8_SA(1, 1), a1 + hstep, voffA);
;             PG8_WAIT_V(8); PG8_WAIT_L(0); PG8_BAR; PG8_MMA(0, 0, At, B0); PG8_MMA(0, 1, At, B1); PG8_BAR; PG8_SCHED;
;             PG8_LDA(At, 0, 1); PG8_STAGE(PG8_SB(0, 0), b2, voffB); PG8_STAGE(PG8_SB(0, 1), b2 + hstep, voffB); PG8_STAGE(PG8_SA(0, 0), a2, voffA);
.LBB0_924:
	s_add_u32 s28, s26, 0xfff80080
	s_addc_u32 s29, s27, -1
	s_add_i32 s51, 0, 0x10000
	s_cmp_eq_u32 s50, 28
	s_cselect_b32 s31, s7, s29
	s_cselect_b32 s30, s8, s28
	v_add_u32_e32 v148, s51, v151
	s_cselect_b32 s29, s19, s49
	s_cselect_b32 s28, s21, s35
	s_add_i32 s54, 0, 0x14000
	ds_read_b128 v[140:143], v148
	ds_read_b128 v[144:147], v148 offset:1024
	ds_read_b128 v[156:159], v148 offset:2048
	ds_read_b128 v[160:163], v148 offset:3072
	v_add_u32_e32 v148, s54, v151
	ds_read_b128 v[164:167], v148
	ds_read_b128 v[168:171], v148 offset:1024
	ds_read_b128 v[172:175], v148 offset:2048
	ds_read_b128 v[176:179], v148 offset:3072
	v_lshl_add_u64 v[212:213], s[26:27], 0, v[136:137]
	s_add_i32 m0, s42, 0xc000
	ds_read_b128 v[180:183], v155
	ds_read_b128 v[184:187], v155 offset:1024
	ds_read_b128 v[188:191], v155 offset:2048
	ds_read_b128 v[192:195], v155 offset:3072
	ds_read_b128 v[196:199], v155 offset:4096
	ds_read_b128 v[200:203], v155 offset:5120
	ds_read_b128 v[204:207], v155 offset:6144
	ds_read_b128 v[208:211], v155 offset:7168
	global_load_lds_dwordx4 v[212:213], off
	v_lshl_add_u64 v[212:213], s[26:27], 0, v[138:139]
	s_add_i32 m0, s42, 0xe000
	s_nop 0
	global_load_lds_dwordx4 v[212:213], off
	s_waitcnt vmcnt(8)
	s_waitcnt lgkmcnt(0)
	s_setprio 1
	s_barrier
	v_mfma_f32_16x16x32_bf16 v[126:129], v[140:143], v[180:183], v[126:129]
	v_mfma_f32_16x16x32_bf16 v[126:129], v[144:147], v[184:187], v[126:129]
	v_mfma_f32_16x16x32_bf16 v[122:125], v[156:159], v[180:183], v[122:125]
	v_mfma_f32_16x16x32_bf16 v[122:125], v[160:163], v[184:187], v[122:125]
	v_mfma_f32_16x16x32_bf16 v[106:109], v[156:159], v[188:191], v[106:109]
	v_mfma_f32_16x16x32_bf16 v[106:109], v[160:163], v[192:195], v[106:109]
	v_mfma_f32_16x16x32_bf16 v[110:113], v[140:143], v[188:191], v[110:113]
	v_mfma_f32_16x16x32_bf16 v[110:113], v[144:147], v[192:195], v[110:113]
	v_mfma_f32_16x16x32_bf16 v[94:97], v[140:143], v[196:199], v[94:97]
	v_mfma_f32_16x16x32_bf16 v[94:97], v[144:147], v[200:203], v[94:97]
	v_mfma_f32_16x16x32_bf16 v[90:93], v[156:159], v[196:199], v[90:93]
	v_mfma_f32_16x16x32_bf16 v[90:93], v[160:163], v[200:203], v[90:93]
	v_mfma_f32_16x16x32_bf16 v[74:77], v[156:159], v[204:207], v[74:77]
	v_mfma_f32_16x16x32_bf16 v[74:77], v[160:163], v[208:211], v[74:77]
	v_mfma_f32_16x16x32_bf16 v[78:81], v[140:143], v[204:207], v[78:81]
	v_mfma_f32_16x16x32_bf16 v[78:81], v[144:147], v[208:211], v[78:81]
	v_mfma_f32_16x16x32_bf16 v[118:121], v[164:167], v[180:183], v[118:121]
	v_mfma_f32_16x16x32_bf16 v[118:121], v[168:171], v[184:187], v[118:121]
	v_mfma_f32_16x16x32_bf16 v[114:117], v[172:175], v[180:183], v[114:117]
	v_mfma_f32_16x16x32_bf16 v[114:117], v[176:179], v[184:187], v[114:117]
	v_mfma_f32_16x16x32_bf16 v[98:101], v[172:175], v[188:191], v[98:101]
	v_mfma_f32_16x16x32_bf16 v[98:101], v[176:179], v[192:195], v[98:101]
	v_mfma_f32_16x16x32_bf16 v[102:105], v[164:167], v[188:191], v[102:105]
	v_mfma_f32_16x16x32_bf16 v[102:105], v[168:171], v[192:195], v[102:105]
	v_mfma_f32_16x16x32_bf16 v[86:89], v[164:167], v[196:199], v[86:89]
	v_mfma_f32_16x16x32_bf16 v[86:89], v[168:171], v[200:203], v[86:89]
	v_mfma_f32_16x16x32_bf16 v[82:85], v[172:175], v[196:199], v[82:85]
	v_mfma_f32_16x16x32_bf16 v[82:85], v[176:179], v[200:203], v[82:85]
	v_mfma_f32_16x16x32_bf16 v[66:69], v[172:175], v[204:207], v[66:69]
	v_mfma_f32_16x16x32_bf16 v[66:69], v[176:179], v[208:211], v[66:69]
	v_mfma_f32_16x16x32_bf16 v[70:73], v[164:167], v[204:207], v[70:73]
	v_mfma_f32_16x16x32_bf16 v[70:73], v[168:171], v[208:211], v[70:73]
	s_setprio 0
	s_barrier
	s_add_i32 s51, s51, s41
	v_lshl_add_u64 v[212:213], s[28:29], 0, v[0:1]
	s_mov_b32 m0, s51
	ds_read_b128 v[180:183], v155 offset:16384
	ds_read_b128 v[184:187], v155 offset:17408
	ds_read_b128 v[188:191], v155 offset:18432
	ds_read_b128 v[192:195], v155 offset:19456
	ds_read_b128 v[196:199], v155 offset:20480
	ds_read_b128 v[200:203], v155 offset:21504
	ds_read_b128 v[204:207], v155 offset:22528
	ds_read_b128 v[208:211], v155 offset:23552
	global_load_lds_dwordx4 v[212:213], off
	s_add_i32 m0, s51, 0x2000
	s_add_u32 s52, s28, 0x80000
	v_lshl_add_u64 v[214:215], s[28:29], 0, v[130:131]
	s_addc_u32 s53, s29, 0
	s_add_i32 s51, s54, s41
	global_load_lds_dwordx4 v[214:215], off
	v_lshl_add_u64 v[216:217], s[52:53], 0, v[0:1]
	s_mov_b32 m0, s51
	v_lshl_add_u64 v[218:219], s[30:31], 0, v[132:133]
	global_load_lds_dwordx4 v[216:217], off
	v_lshl_add_u64 v[216:217], s[52:53], 0, v[130:131]
	s_add_i32 m0, s51, 0x2000
	s_nop 0
	global_load_lds_dwordx4 v[216:217], off
	v_lshl_add_u64 v[216:217], s[30:31], 0, v[134:135]
	s_mov_b32 m0, s42
	s_nop 0
	global_load_lds_dwordx4 v[216:217], off
	s_mov_b32 m0, s43
	s_nop 0
	global_load_lds_dwordx4 v[218:219], off
	s_waitcnt vmcnt(8)
	s_waitcnt lgkmcnt(0)
	s_setprio 1
	s_barrier
; #define PG8_STAGE(bufoff, gbase, voff) do { _Pragma("unroll") for (int _i = 0; _i < 2; ++_i) \
;         __builtin_amdgcn_global_load_lds((const unsigned*)((const char*)(gbase) + (voff)[_i]), (LAS unsigned*)(lds + (bufoff) + ldsw + _i * 8192), 16, 0, 0); } while (0)
; #define PG8_LDA(dst, b, h) do { _Pragma("unroll") for (int m = 0; m < 4; ++m) _Pragma("unroll") for (int k = 0; k < 2; ++k) dst[m][k] = *(const LAS bf16x8*)(lds + PG8_SA(b, h) + aoff + m * 2048 + k * 1024); } while (0)
; #define PG8_LDB(dst, b, h) do { _Pragma("unroll") for (int n = 0; n < 2; ++n) _Pragma("unroll") for (int k = 0; k < 2; ++k) dst[n][k] = *(const LAS bf16x8*)(lds + PG8_SB(b, h) + boff + n * 2048 + k * 1024); } while (0)
; #define PG8_MMA(ai, bj, At, Bt) do { __builtin_amdgcn_s_setprio(1); _Pragma("unroll") for (int m = 0; m < 4; ++m) _Pragma("unroll") for (int n = 0; n < 2; ++n) _Pragma("unroll") for (int k = 0; k < 2; ++k) \
;         acc[ai][bj][m][n] = __builtin_amdgcn_mfma_f32_16x16x32_bf16(Bt[n][k], At[m][k], acc[ai][bj][m][n], 0, 0, 0); __builtin_amdgcn_s_setprio(0); } while (0)
; #define PG8_WAIT_V(n) asm volatile("s_waitcnt vmcnt(" #n ")" ::: "memory")
; #define PG8_WAIT_L(n) asm volatile("s_waitcnt lgkmcnt(" #n ")" ::: "memory")
; #define PG8_BAR __builtin_amdgcn_s_barrier()
; #define PG8_SCHED __builtin_amdgcn_sched_barrier(0)
; template <class Epi, class Sched, bool ALIGN_EPI = false, bool SP2 = false>
; __device__ __forceinline__ void gemm_phase(LAS unsigned char* lds, const Gemm g, const Sched& S, const Epi& E) {
;     ...
;             PG8_WAIT_V(8); PG8_WAIT_L(0); PG8_BAR; PG8_MMA(1, 0, At, B0); PG8_MMA(1, 1, At, B1); PG8_BAR; PG8_SCHED;
;             PG8_LDB(B0, 1, 0); PG8_LDB(B1, 1, 1); PG8_SCHED; PG8_LDA(At, 1, 0); PG8_STAGE(PG8_SA(0, 1), a2 + hstep, voffA);
;             PG8_WAIT_V(8); PG8_WAIT_L(0); PG8_BAR; PG8_MMA(0, 0, At, B0); PG8_MMA(0, 1, At, B1); PG8_BAR; PG8_SCHED;
	v_mfma_f32_16x16x32_bf16 v[62:65], v[140:143], v[180:183], v[62:65]
	v_mfma_f32_16x16x32_bf16 v[62:65], v[144:147], v[184:187], v[62:65]
	v_mfma_f32_16x16x32_bf16 v[58:61], v[156:159], v[180:183], v[58:61]
	v_mfma_f32_16x16x32_bf16 v[58:61], v[160:163], v[184:187], v[58:61]
	v_mfma_f32_16x16x32_bf16 v[42:45], v[156:159], v[188:191], v[42:45]
	v_mfma_f32_16x16x32_bf16 v[42:45], v[160:163], v[192:195], v[42:45]
	v_mfma_f32_16x16x32_bf16 v[46:49], v[140:143], v[188:191], v[46:49]
	v_mfma_f32_16x16x32_bf16 v[46:49], v[144:147], v[192:195], v[46:49]
	v_mfma_f32_16x16x32_bf16 v[30:33], v[140:143], v[196:199], v[30:33]
	v_mfma_f32_16x16x32_bf16 v[30:33], v[144:147], v[200:203], v[30:33]
	v_mfma_f32_16x16x32_bf16 v[26:29], v[156:159], v[196:199], v[26:29]
	v_mfma_f32_16x16x32_bf16 v[26:29], v[160:163], v[200:203], v[26:29]
	v_mfma_f32_16x16x32_bf16 v[10:13], v[156:159], v[204:207], v[10:13]
	v_mfma_f32_16x16x32_bf16 v[10:13], v[160:163], v[208:211], v[10:13]
	v_mfma_f32_16x16x32_bf16 v[14:17], v[140:143], v[204:207], v[14:17]
	v_mfma_f32_16x16x32_bf16 v[14:17], v[144:147], v[208:211], v[14:17]
	v_mfma_f32_16x16x32_bf16 v[54:57], v[164:167], v[180:183], v[54:57]
	v_mfma_f32_16x16x32_bf16 v[54:57], v[168:171], v[184:187], v[54:57]
	v_mfma_f32_16x16x32_bf16 v[50:53], v[172:175], v[180:183], v[50:53]
	v_mfma_f32_16x16x32_bf16 v[50:53], v[176:179], v[184:187], v[50:53]
	v_mfma_f32_16x16x32_bf16 v[34:37], v[172:175], v[188:191], v[34:37]
	v_mfma_f32_16x16x32_bf16 v[34:37], v[176:179], v[192:195], v[34:37]
	v_mfma_f32_16x16x32_bf16 v[38:41], v[164:167], v[188:191], v[38:41]
	v_mfma_f32_16x16x32_bf16 v[38:41], v[168:171], v[192:195], v[38:41]
	v_mfma_f32_16x16x32_bf16 v[22:25], v[164:167], v[196:199], v[22:25]
	v_mfma_f32_16x16x32_bf16 v[22:25], v[168:171], v[200:203], v[22:25]
	v_mfma_f32_16x16x32_bf16 v[18:21], v[172:175], v[196:199], v[18:21]
	v_mfma_f32_16x16x32_bf16 v[18:21], v[176:179], v[200:203], v[18:21]
	v_mfma_f32_16x16x32_bf16 v[2:5], v[172:175], v[204:207], v[2:5]
	v_mfma_f32_16x16x32_bf16 v[2:5], v[176:179], v[208:211], v[2:5]
	v_mfma_f32_16x16x32_bf16 v[6:9], v[164:167], v[204:207], v[6:9]
	v_mfma_f32_16x16x32_bf16 v[6:9], v[168:171], v[208:211], v[6:9]
	s_setprio 0
	s_barrier
	s_add_i32 s51, 0, 0x18000
	v_add_u32_e32 v148, s51, v151
	s_add_i32 s52, 0, 0x1c000
	ds_read_b128 v[140:143], v148
	ds_read_b128 v[144:147], v148 offset:1024
	ds_read_b128 v[156:159], v148 offset:2048
	ds_read_b128 v[160:163], v148 offset:3072
	v_add_u32_e32 v148, s52, v151
	ds_read_b128 v[164:167], v148
	ds_read_b128 v[168:171], v148 offset:1024
	ds_read_b128 v[172:175], v148 offset:2048
	ds_read_b128 v[176:179], v148 offset:3072
	s_add_u32 s30, s30, 0x80000
	s_addc_u32 s31, s31, 0
	s_mov_b32 m0, s44
	v_lshl_add_u64 v[220:221], s[30:31], 0, v[134:135]
	ds_read_b128 v[180:183], v155 offset:32768
	ds_read_b128 v[184:187], v155 offset:33792
	ds_read_b128 v[188:191], v155 offset:34816
	ds_read_b128 v[192:195], v155 offset:35840
	ds_read_b128 v[196:199], v155 offset:36864
	ds_read_b128 v[200:203], v155 offset:37888
	ds_read_b128 v[204:207], v155 offset:38912
	ds_read_b128 v[208:211], v155 offset:39936
	global_load_lds_dwordx4 v[220:221], off
	v_lshl_add_u64 v[220:221], s[30:31], 0, v[132:133]
	s_mov_b32 m0, s45
	s_nop 0
	global_load_lds_dwordx4 v[220:221], off
	s_waitcnt vmcnt(8)
	s_waitcnt lgkmcnt(0)
	s_setprio 1
	s_barrier
	v_mfma_f32_16x16x32_bf16 v[126:129], v[140:143], v[180:183], v[126:129]
	v_mfma_f32_16x16x32_bf16 v[126:129], v[144:147], v[184:187], v[126:129]
	v_mfma_f32_16x16x32_bf16 v[122:125], v[156:159], v[180:183], v[122:125]
	v_mfma_f32_16x16x32_bf16 v[122:125], v[160:163], v[184:187], v[122:125]
	v_mfma_f32_16x16x32_bf16 v[106:109], v[156:159], v[188:191], v[106:109]
	v_mfma_f32_16x16x32_bf16 v[106:109], v[160:163], v[192:195], v[106:109]
	v_mfma_f32_16x16x32_bf16 v[110:113], v[140:143], v[188:191], v[110:113]
	v_mfma_f32_16x16x32_bf16 v[110:113], v[144:147], v[192:195], v[110:113]
	v_mfma_f32_16x16x32_bf16 v[94:97], v[140:143], v[196:199], v[94:97]
	v_mfma_f32_16x16x32_bf16 v[94:97], v[144:147], v[200:203], v[94:97]
	v_mfma_f32_16x16x32_bf16 v[90:93], v[156:159], v[196:199], v[90:93]
	v_mfma_f32_16x16x32_bf16 v[90:93], v[160:163], v[200:203], v[90:93]
	v_mfma_f32_16x16x32_bf16 v[74:77], v[156:159], v[204:207], v[74:77]
	v_mfma_f32_16x16x32_bf16 v[74:77], v[160:163], v[208:211], v[74:77]
	v_mfma_f32_16x16x32_bf16 v[78:81], v[140:143], v[204:207], v[78:81]
	v_mfma_f32_16x16x32_bf16 v[78:81], v[144:147], v[208:211], v[78:81]
	v_mfma_f32_16x16x32_bf16 v[118:121], v[164:167], v[180:183], v[118:121]
	v_mfma_f32_16x16x32_bf16 v[118:121], v[168:171], v[184:187], v[118:121]
	v_mfma_f32_16x16x32_bf16 v[114:117], v[172:175], v[180:183], v[114:117]
	v_mfma_f32_16x16x32_bf16 v[114:117], v[176:179], v[184:187], v[114:117]
	v_mfma_f32_16x16x32_bf16 v[98:101], v[172:175], v[188:191], v[98:101]
	v_mfma_f32_16x16x32_bf16 v[98:101], v[176:179], v[192:195], v[98:101]
	v_mfma_f32_16x16x32_bf16 v[102:105], v[164:167], v[188:191], v[102:105]
	v_mfma_f32_16x16x32_bf16 v[102:105], v[168:171], v[192:195], v[102:105]
	v_mfma_f32_16x16x32_bf16 v[86:89], v[164:167], v[196:199], v[86:89]
	v_mfma_f32_16x16x32_bf16 v[86:89], v[168:171], v[200:203], v[86:89]
	v_mfma_f32_16x16x32_bf16 v[82:85], v[172:175], v[196:199], v[82:85]
	v_mfma_f32_16x16x32_bf16 v[82:85], v[176:179], v[200:203], v[82:85]
	v_mfma_f32_16x16x32_bf16 v[66:69], v[172:175], v[204:207], v[66:69]
	v_mfma_f32_16x16x32_bf16 v[66:69], v[176:179], v[208:211], v[66:69]
	v_mfma_f32_16x16x32_bf16 v[70:73], v[164:167], v[204:207], v[70:73]
	v_mfma_f32_16x16x32_bf16 v[70:73], v[168:171], v[208:211], v[70:73]
	s_setprio 0
	s_barrier
; #define PG8_STAGE(bufoff, gbase, voff) do { _Pragma("unroll") for (int _i = 0; _i < 2; ++_i) \
;         __builtin_amdgcn_global_load_lds((const unsigned*)((const char*)(gbase) + (voff)[_i]), (LAS unsigned*)(lds + (bufoff) + ldsw + _i * 8192), 16, 0, 0); } while (0)
; #define PG8_LDA(dst, b, h) do { _Pragma("unroll") for (int m = 0; m < 4; ++m) _Pragma("unroll") for (int k = 0; k < 2; ++k) dst[m][k] = *(const LAS bf16x8*)(lds + PG8_SA(b, h) + aoff + m * 2048 + k * 1024); } while (0)
; #define PG8_MMA(ai, bj, At, Bt) do { __builtin_amdgcn_s_setprio(1); _Pragma("unroll") for (int m = 0; m < 4; ++m) _Pragma("unroll") for (int n = 0; n < 2; ++n) _Pragma("unroll") for (int k = 0; k < 2; ++k) \
;         acc[ai][bj][m][n] = __builtin_amdgcn_mfma_f32_16x16x32_bf16(Bt[n][k], At[m][k], acc[ai][bj][m][n], 0, 0, 0); __builtin_amdgcn_s_setprio(0); } while (0)
; #define PG8_WAIT_V(n) asm volatile("s_waitcnt vmcnt(" #n ")" ::: "memory")
; #define PG8_WAIT_L(n) asm volatile("s_waitcnt lgkmcnt(" #n ")" ::: "memory")
; #define PG8_BAR __builtin_amdgcn_s_barrier()
; #define PG8_SCHED __builtin_amdgcn_sched_barrier(0)
; template <class Epi, class Sched, bool ALIGN_EPI = false, bool SP2 = false>
; __device__ __forceinline__ void gemm_phase(LAS unsigned char* lds, const Gemm g, const Sched& S, const Epi& E) {
;     ...
;             PG8_WAIT_V(8); PG8_WAIT_L(0); PG8_BAR; PG8_MMA(0, 0, At, B0); PG8_MMA(0, 1, At, B1); PG8_BAR; PG8_SCHED;
;             PG8_LDA(At, 1, 1); PG8_STAGE(PG8_SB(1, 0), b3, voffB); PG8_STAGE(PG8_SB(1, 1), b3 + hstep, voffB); PG8_STAGE(PG8_SA(1, 0), a3, voffA);
;             PG8_WAIT_V(8); PG8_WAIT_L(0); PG8_BAR; PG8_MMA(1, 0, At, B0); PG8_MMA(1, 1, At, B1); PG8_BAR; PG8_SCHED;
;     ...
;         if constexpr (ALIGN_EPI) { if (wr == 0) PG8_BAR; }
	s_add_i32 s30, s51, s41
	v_lshl_add_u64 v[212:213], v[212:213], 0, s[12:13]
	s_mov_b32 m0, s30
	ds_read_b128 v[180:183], v155 offset:49152
	ds_read_b128 v[184:187], v155 offset:50176
	ds_read_b128 v[188:191], v155 offset:51200
	ds_read_b128 v[192:195], v155 offset:52224
	ds_read_b128 v[196:199], v155 offset:53248
	ds_read_b128 v[200:203], v155 offset:54272
	ds_read_b128 v[204:207], v155 offset:55296
	ds_read_b128 v[208:211], v155 offset:56320
	global_load_lds_dwordx4 v[212:213], off
	s_add_i32 m0, s30, 0x2000
	s_add_u32 s28, s28, 0x80080
	v_lshl_add_u64 v[212:213], v[214:215], 0, s[12:13]
	s_addc_u32 s29, s29, 0
	s_add_i32 s30, s52, s41
	global_load_lds_dwordx4 v[212:213], off
	v_lshl_add_u64 v[212:213], s[28:29], 0, v[0:1]
	s_mov_b32 m0, s30
	s_nop 0
	global_load_lds_dwordx4 v[212:213], off
	v_lshl_add_u64 v[212:213], s[28:29], 0, v[130:131]
	s_add_i32 m0, s30, 0x2000
	s_nop 0
	global_load_lds_dwordx4 v[212:213], off
	v_lshl_add_u64 v[212:213], v[216:217], 0, s[12:13]
	s_mov_b32 m0, s46
	s_nop 0
	global_load_lds_dwordx4 v[212:213], off
	v_lshl_add_u64 v[212:213], v[218:219], 0, s[12:13]
	s_mov_b32 m0, s47
	s_nop 0
	global_load_lds_dwordx4 v[212:213], off
	s_waitcnt vmcnt(8)
	s_waitcnt lgkmcnt(0)
	s_setprio 1
	s_barrier
	v_mfma_f32_16x16x32_bf16 v[62:65], v[140:143], v[180:183], v[62:65]
	v_mfma_f32_16x16x32_bf16 v[62:65], v[144:147], v[184:187], v[62:65]
	v_mfma_f32_16x16x32_bf16 v[58:61], v[156:159], v[180:183], v[58:61]
	v_mfma_f32_16x16x32_bf16 v[58:61], v[160:163], v[184:187], v[58:61]
	v_mfma_f32_16x16x32_bf16 v[42:45], v[156:159], v[188:191], v[42:45]
	v_mfma_f32_16x16x32_bf16 v[42:45], v[160:163], v[192:195], v[42:45]
	v_mfma_f32_16x16x32_bf16 v[46:49], v[140:143], v[188:191], v[46:49]
	v_mfma_f32_16x16x32_bf16 v[46:49], v[144:147], v[192:195], v[46:49]
	v_mfma_f32_16x16x32_bf16 v[30:33], v[140:143], v[196:199], v[30:33]
	v_mfma_f32_16x16x32_bf16 v[30:33], v[144:147], v[200:203], v[30:33]
	v_mfma_f32_16x16x32_bf16 v[26:29], v[156:159], v[196:199], v[26:29]
	v_mfma_f32_16x16x32_bf16 v[26:29], v[160:163], v[200:203], v[26:29]
	v_mfma_f32_16x16x32_bf16 v[10:13], v[156:159], v[204:207], v[10:13]
	v_mfma_f32_16x16x32_bf16 v[10:13], v[160:163], v[208:211], v[10:13]
	v_mfma_f32_16x16x32_bf16 v[14:17], v[140:143], v[204:207], v[14:17]
	v_mfma_f32_16x16x32_bf16 v[14:17], v[144:147], v[208:211], v[14:17]
	v_mfma_f32_16x16x32_bf16 v[54:57], v[164:167], v[180:183], v[54:57]
	v_mfma_f32_16x16x32_bf16 v[54:57], v[168:171], v[184:187], v[54:57]
	v_mfma_f32_16x16x32_bf16 v[50:53], v[172:175], v[180:183], v[50:53]
	v_mfma_f32_16x16x32_bf16 v[50:53], v[176:179], v[184:187], v[50:53]
	v_mfma_f32_16x16x32_bf16 v[34:37], v[172:175], v[188:191], v[34:37]
	v_mfma_f32_16x16x32_bf16 v[34:37], v[176:179], v[192:195], v[34:37]
	v_mfma_f32_16x16x32_bf16 v[38:41], v[164:167], v[188:191], v[38:41]
	v_mfma_f32_16x16x32_bf16 v[38:41], v[168:171], v[192:195], v[38:41]
	v_mfma_f32_16x16x32_bf16 v[22:25], v[164:167], v[196:199], v[22:25]
	v_mfma_f32_16x16x32_bf16 v[22:25], v[168:171], v[200:203], v[22:25]
	v_mfma_f32_16x16x32_bf16 v[18:21], v[172:175], v[196:199], v[18:21]
	v_mfma_f32_16x16x32_bf16 v[18:21], v[176:179], v[200:203], v[18:21]
	v_mfma_f32_16x16x32_bf16 v[2:5], v[172:175], v[204:207], v[2:5]
	v_mfma_f32_16x16x32_bf16 v[2:5], v[176:179], v[208:211], v[2:5]
	v_mfma_f32_16x16x32_bf16 v[6:9], v[164:167], v[204:207], v[6:9]
	v_mfma_f32_16x16x32_bf16 v[6:9], v[168:171], v[208:211], v[6:9]
	s_setprio 0
	s_barrier
	s_add_i32 s50, s50, 2
	s_add_u32 s26, s26, 0x100
	s_addc_u32 s27, s27, 0
	s_add_u32 s35, s35, 0x100
	s_addc_u32 s49, s49, 0
	s_cmp_gt_u32 s50, 29
	s_cbranch_scc0 .LBB0_924
	s_and_b64 vcc, exec, s[16:17]
	s_cbranch_vccz .LBB0_927
	s_barrier

; #define PG8_STAGE(bufoff, gbase, voff) do { _Pragma("unroll") for (int _i = 0; _i < 2; ++_i) \
;         __builtin_amdgcn_global_load_lds((const unsigned*)((const char*)(gbase) + (voff)[_i]), (LAS unsigned*)(lds + (bufoff) + ldsw + _i * 8192), 16, 0, 0); } while (0)
; #define PG8_LDA(dst, b, h) do { _Pragma("unroll") for (int m = 0; m < 4; ++m) _Pragma("unroll") for (int k = 0; k < 2; ++k) dst[m][k] = *(const LAS bf16x8*)(lds + PG8_SA(b, h) + aoff + m * 2048 + k * 1024); } while (0)
; #define PG8_LDB(dst, b, h) do { _Pragma("unroll") for (int n = 0; n < 2; ++n) _Pragma("unroll") for (int k = 0; k < 2; ++k) dst[n][k] = *(const LAS bf16x8*)(lds + PG8_SB(b, h) + boff + n * 2048 + k * 1024); } while (0)
; #define PG8_MMA(ai, bj, At, Bt) do { __builtin_amdgcn_s_setprio(1); _Pragma("unroll") for (int m = 0; m < 4; ++m) _Pragma("unroll") for (int n = 0; n < 2; ++n) _Pragma("unroll") for (int k = 0; k < 2; ++k) \
;         acc[ai][bj][m][n] = __builtin_amdgcn_mfma_f32_16x16x32_bf16(Bt[n][k], At[m][k], acc[ai][bj][m][n], 0, 0, 0); __builtin_amdgcn_s_setprio(0); } while (0)
; #define PG8_WAIT_V(n) asm volatile("s_waitcnt vmcnt(" #n ")" ::: "memory")
; #define PG8_WAIT_L(n) asm volatile("s_waitcnt lgkmcnt(" #n ")" ::: "memory")
; #define PG8_BAR __builtin_amdgcn_s_barrier()
; #define PG8_SCHED __builtin_amdgcn_sched_barrier(0)
; template <class Epi, class Sched, bool ALIGN_EPI = false, bool SP2 = false>
; __device__ __forceinline__ void gemm_phase(LAS unsigned char* lds, const Gemm g, const Sched& S, const Epi& E) {
;     ...
;             const bool last = (t == nt - 2);
;             const char* a1 = cA + (size_t)(t + 1) * kstep;
;             const char* a2 = last ? nA : cA + (size_t)(t + 2) * kstep; const char* b2 = last ? nB : cB + (size_t)(t + 2) * kstep;
;             const char* a3 = a2 + kstep; const char* b3 = b2 + kstep;
;             if (last && has_next) S.a_ready(nxt);
;             if constexpr (SP2) {
;             PG8_LDB(B0, 0, 0); PG8_LDB(B1, 0, 1); PG8_SCHED; PG8_LDA(At, 0, 0); PG8_STAGE(PG8_SA(1, 1), a1 + hstep, voffA);
;             PG8_WAIT_V(8); PG8_WAIT_L(0); PG8_BAR; PG8_MMA(0, 0, At, B0); PG8_MMA(0, 1, At, B1); PG8_BAR; PG8_SCHED;
;             PG8_LDA(At, 0, 1); PG8_STAGE(PG8_SB(0, 0), b2, voffB); PG8_STAGE(PG8_SB(0, 1), b2 + hstep, voffB); PG8_STAGE(PG8_SA(0, 0), a2, voffA);
.LBB0_1007:
	s_add_u32 s24, s22, 0x100
	s_addc_u32 s25, s23, 0
	s_add_i32 s49, 0, 0x10000
	s_cmpk_eq_i32 s48, 0x54
	s_cselect_b32 s29, s1, s25
	s_cselect_b32 s28, s0, s24
	s_cselect_b32 s27, s21, s47
	s_cselect_b32 s26, s20, s46
	s_add_i32 s50, 0, 0x14000
	v_add_u32_e32 v126, s49, v247
	v_add_u32_e32 v158, s50, v247
	ds_read_b128 v[90:93], v126
	ds_read_b128 v[102:105], v126 offset:1024
	ds_read_b128 v[114:117], v126 offset:2048
	ds_read_b128 v[126:129], v126 offset:3072
	ds_read_b128 v[138:141], v158
	ds_read_b128 v[142:145], v158 offset:1024
	ds_read_b128 v[154:157], v158 offset:2048
	ds_read_b128 v[158:161], v158 offset:3072
	v_lshl_add_u64 v[204:205], s[22:23], 0, v[200:201]
	s_add_i32 m0, s8, 0xc000
	ds_read_b128 v[162:165], v249
	ds_read_b128 v[166:169], v249 offset:1024
	ds_read_b128 v[170:173], v249 offset:2048
	ds_read_b128 v[174:177], v249 offset:3072
	ds_read_b128 v[178:181], v249 offset:4096
	ds_read_b128 v[182:185], v249 offset:5120
	ds_read_b128 v[186:189], v249 offset:6144
	ds_read_b128 v[190:193], v249 offset:7168
	global_load_lds_dwordx4 v[204:205], off
	v_lshl_add_u64 v[204:205], s[22:23], 0, v[202:203]
	s_add_i32 m0, s8, 0xe000
	s_nop 0
	global_load_lds_dwordx4 v[204:205], off
	s_waitcnt vmcnt(8)
	s_waitcnt lgkmcnt(0)
	s_setprio 1
	s_barrier
	v_mfma_f32_16x16x32_bf16 v[150:153], v[90:93], v[162:165], v[150:153]
	v_mfma_f32_16x16x32_bf16 v[150:153], v[102:105], v[166:169], v[150:153]
	v_mfma_f32_16x16x32_bf16 v[146:149], v[114:117], v[162:165], v[146:149]
	v_mfma_f32_16x16x32_bf16 v[146:149], v[126:129], v[166:169], v[146:149]
	v_mfma_f32_16x16x32_bf16 v[118:121], v[114:117], v[170:173], v[118:121]
	v_mfma_f32_16x16x32_bf16 v[118:121], v[126:129], v[174:177], v[118:121]
	v_mfma_f32_16x16x32_bf16 v[122:125], v[90:93], v[170:173], v[122:125]
	v_mfma_f32_16x16x32_bf16 v[122:125], v[102:105], v[174:177], v[122:125]
	v_mfma_f32_16x16x32_bf16 v[98:101], v[90:93], v[178:181], v[98:101]
	v_mfma_f32_16x16x32_bf16 v[98:101], v[102:105], v[182:185], v[98:101]
	v_mfma_f32_16x16x32_bf16 v[94:97], v[114:117], v[178:181], v[94:97]
	v_mfma_f32_16x16x32_bf16 v[94:97], v[126:129], v[182:185], v[94:97]
	v_mfma_f32_16x16x32_bf16 v[74:77], v[114:117], v[186:189], v[74:77]
	v_mfma_f32_16x16x32_bf16 v[74:77], v[126:129], v[190:193], v[74:77]
	v_mfma_f32_16x16x32_bf16 v[78:81], v[90:93], v[186:189], v[78:81]
	v_mfma_f32_16x16x32_bf16 v[78:81], v[102:105], v[190:193], v[78:81]
	v_mfma_f32_16x16x32_bf16 v[134:137], v[138:141], v[162:165], v[134:137]
	v_mfma_f32_16x16x32_bf16 v[134:137], v[142:145], v[166:169], v[134:137]
	v_mfma_f32_16x16x32_bf16 v[130:133], v[154:157], v[162:165], v[130:133]
	v_mfma_f32_16x16x32_bf16 v[130:133], v[158:161], v[166:169], v[130:133]
	v_mfma_f32_16x16x32_bf16 v[106:109], v[154:157], v[170:173], v[106:109]
	v_mfma_f32_16x16x32_bf16 v[106:109], v[158:161], v[174:177], v[106:109]
	v_mfma_f32_16x16x32_bf16 v[110:113], v[138:141], v[170:173], v[110:113]
	v_mfma_f32_16x16x32_bf16 v[110:113], v[142:145], v[174:177], v[110:113]
	v_mfma_f32_16x16x32_bf16 v[86:89], v[138:141], v[178:181], v[86:89]
	v_mfma_f32_16x16x32_bf16 v[86:89], v[142:145], v[182:185], v[86:89]
	v_mfma_f32_16x16x32_bf16 v[82:85], v[154:157], v[178:181], v[82:85]
	v_mfma_f32_16x16x32_bf16 v[82:85], v[158:161], v[182:185], v[82:85]
	v_mfma_f32_16x16x32_bf16 v[66:69], v[154:157], v[186:189], v[66:69]
	v_mfma_f32_16x16x32_bf16 v[66:69], v[158:161], v[190:193], v[66:69]
	v_mfma_f32_16x16x32_bf16 v[70:73], v[138:141], v[186:189], v[70:73]
	v_mfma_f32_16x16x32_bf16 v[70:73], v[142:145], v[190:193], v[70:73]
	s_setprio 0
	s_barrier
	s_add_i32 s22, s49, s7
	v_lshl_add_u64 v[204:205], s[26:27], 0, v[0:1]
	s_mov_b32 m0, s22
	ds_read_b128 v[162:165], v249 offset:16384
	ds_read_b128 v[166:169], v249 offset:17408
	ds_read_b128 v[170:173], v249 offset:18432
	ds_read_b128 v[174:177], v249 offset:19456
	ds_read_b128 v[178:181], v249 offset:20480
	ds_read_b128 v[182:185], v249 offset:21504
	ds_read_b128 v[186:189], v249 offset:22528
	ds_read_b128 v[190:193], v249 offset:23552
	global_load_lds_dwordx4 v[204:205], off
	s_add_i32 m0, s22, 0x2000
	s_add_u32 s22, s26, 0x160000
	v_lshl_add_u64 v[206:207], s[26:27], 0, v[194:195]
	s_addc_u32 s23, s27, 0
	s_add_i32 s49, s50, s7
	global_load_lds_dwordx4 v[206:207], off
	v_lshl_add_u64 v[208:209], s[22:23], 0, v[0:1]
	s_mov_b32 m0, s49
	v_lshl_add_u64 v[210:211], s[28:29], 0, v[196:197]
	global_load_lds_dwordx4 v[208:209], off
	v_lshl_add_u64 v[208:209], s[22:23], 0, v[194:195]
	s_add_i32 m0, s49, 0x2000
	s_nop 0
	global_load_lds_dwordx4 v[208:209], off
	v_lshl_add_u64 v[208:209], s[28:29], 0, v[198:199]
	s_mov_b32 m0, s8
	s_nop 0
	global_load_lds_dwordx4 v[208:209], off
	s_mov_b32 m0, s9
	s_nop 0
	global_load_lds_dwordx4 v[210:211], off
	s_waitcnt vmcnt(8)
	s_waitcnt lgkmcnt(0)
	s_setprio 1
	s_barrier
; #define PG8_STAGE(bufoff, gbase, voff) do { _Pragma("unroll") for (int _i = 0; _i < 2; ++_i) \
;         __builtin_amdgcn_global_load_lds((const unsigned*)((const char*)(gbase) + (voff)[_i]), (LAS unsigned*)(lds + (bufoff) + ldsw + _i * 8192), 16, 0, 0); } while (0)
; #define PG8_LDA(dst, b, h) do { _Pragma("unroll") for (int m = 0; m < 4; ++m) _Pragma("unroll") for (int k = 0; k < 2; ++k) dst[m][k] = *(const LAS bf16x8*)(lds + PG8_SA(b, h) + aoff + m * 2048 + k * 1024); } while (0)
; #define PG8_LDB(dst, b, h) do { _Pragma("unroll") for (int n = 0; n < 2; ++n) _Pragma("unroll") for (int k = 0; k < 2; ++k) dst[n][k] = *(const LAS bf16x8*)(lds + PG8_SB(b, h) + boff + n * 2048 + k * 1024); } while (0)
; #define PG8_MMA(ai, bj, At, Bt) do { __builtin_amdgcn_s_setprio(1); _Pragma("unroll") for (int m = 0; m < 4; ++m) _Pragma("unroll") for (int n = 0; n < 2; ++n) _Pragma("unroll") for (int k = 0; k < 2; ++k) \
;         acc[ai][bj][m][n] = __builtin_amdgcn_mfma_f32_16x16x32_bf16(Bt[n][k], At[m][k], acc[ai][bj][m][n], 0, 0, 0); __builtin_amdgcn_s_setprio(0); } while (0)
; #define PG8_WAIT_V(n) asm volatile("s_waitcnt vmcnt(" #n ")" ::: "memory")
; #define PG8_WAIT_L(n) asm volatile("s_waitcnt lgkmcnt(" #n ")" ::: "memory")
; #define PG8_BAR __builtin_amdgcn_s_barrier()
; #define PG8_SCHED __builtin_amdgcn_sched_barrier(0)
; template <class Epi, class Sched, bool ALIGN_EPI = false, bool SP2 = false>
; __device__ __forceinline__ void gemm_phase(LAS unsigned char* lds, const Gemm g, const Sched& S, const Epi& E) {
;     ...
;             PG8_WAIT_V(8); PG8_WAIT_L(0); PG8_BAR; PG8_MMA(1, 0, At, B0); PG8_MMA(1, 1, At, B1); PG8_BAR; PG8_SCHED;
;             PG8_LDB(B0, 1, 0); PG8_LDB(B1, 1, 1); PG8_SCHED; PG8_LDA(At, 1, 0); PG8_STAGE(PG8_SA(0, 1), a2 + hstep, voffA);
;             PG8_WAIT_V(8); PG8_WAIT_L(0); PG8_BAR; PG8_MMA(0, 0, At, B0); PG8_MMA(0, 1, At, B1); PG8_BAR; PG8_SCHED;
	v_mfma_f32_16x16x32_bf16 v[62:65], v[90:93], v[162:165], v[62:65]
	v_mfma_f32_16x16x32_bf16 v[62:65], v[102:105], v[166:169], v[62:65]
	v_mfma_f32_16x16x32_bf16 v[58:61], v[114:117], v[162:165], v[58:61]
	v_mfma_f32_16x16x32_bf16 v[58:61], v[126:129], v[166:169], v[58:61]
	v_mfma_f32_16x16x32_bf16 v[42:45], v[114:117], v[170:173], v[42:45]
	v_mfma_f32_16x16x32_bf16 v[42:45], v[126:129], v[174:177], v[42:45]
	v_mfma_f32_16x16x32_bf16 v[46:49], v[90:93], v[170:173], v[46:49]
	v_mfma_f32_16x16x32_bf16 v[46:49], v[102:105], v[174:177], v[46:49]
	v_mfma_f32_16x16x32_bf16 v[30:33], v[90:93], v[178:181], v[30:33]
	v_mfma_f32_16x16x32_bf16 v[30:33], v[102:105], v[182:185], v[30:33]
	v_mfma_f32_16x16x32_bf16 v[26:29], v[114:117], v[178:181], v[26:29]
	v_mfma_f32_16x16x32_bf16 v[26:29], v[126:129], v[182:185], v[26:29]
	v_mfma_f32_16x16x32_bf16 v[10:13], v[114:117], v[186:189], v[10:13]
	v_mfma_f32_16x16x32_bf16 v[10:13], v[126:129], v[190:193], v[10:13]
	v_mfma_f32_16x16x32_bf16 v[14:17], v[90:93], v[186:189], v[14:17]
	v_mfma_f32_16x16x32_bf16 v[14:17], v[102:105], v[190:193], v[14:17]
	v_mfma_f32_16x16x32_bf16 v[54:57], v[138:141], v[162:165], v[54:57]
	v_mfma_f32_16x16x32_bf16 v[54:57], v[142:145], v[166:169], v[54:57]
	v_mfma_f32_16x16x32_bf16 v[50:53], v[154:157], v[162:165], v[50:53]
	v_mfma_f32_16x16x32_bf16 v[50:53], v[158:161], v[166:169], v[50:53]
	v_mfma_f32_16x16x32_bf16 v[34:37], v[154:157], v[170:173], v[34:37]
	v_mfma_f32_16x16x32_bf16 v[34:37], v[158:161], v[174:177], v[34:37]
	v_mfma_f32_16x16x32_bf16 v[38:41], v[138:141], v[170:173], v[38:41]
	v_mfma_f32_16x16x32_bf16 v[38:41], v[142:145], v[174:177], v[38:41]
	v_mfma_f32_16x16x32_bf16 v[22:25], v[138:141], v[178:181], v[22:25]
	v_mfma_f32_16x16x32_bf16 v[22:25], v[142:145], v[182:185], v[22:25]
	v_mfma_f32_16x16x32_bf16 v[18:21], v[154:157], v[178:181], v[18:21]
	v_mfma_f32_16x16x32_bf16 v[18:21], v[158:161], v[182:185], v[18:21]
	v_mfma_f32_16x16x32_bf16 v[2:5], v[154:157], v[186:189], v[2:5]
	v_mfma_f32_16x16x32_bf16 v[2:5], v[158:161], v[190:193], v[2:5]
	v_mfma_f32_16x16x32_bf16 v[6:9], v[138:141], v[186:189], v[6:9]
	v_mfma_f32_16x16x32_bf16 v[6:9], v[142:145], v[190:193], v[6:9]
	s_setprio 0
	s_barrier
	s_add_i32 s49, 0, 0x18000
	s_add_i32 s50, 0, 0x1c000
	v_add_u32_e32 v126, s49, v247
	v_add_u32_e32 v158, s50, v247
	ds_read_b128 v[90:93], v126
	ds_read_b128 v[102:105], v126 offset:1024
	ds_read_b128 v[114:117], v126 offset:2048
	ds_read_b128 v[126:129], v126 offset:3072
	ds_read_b128 v[138:141], v158
	ds_read_b128 v[142:145], v158 offset:1024
	ds_read_b128 v[154:157], v158 offset:2048
	ds_read_b128 v[158:161], v158 offset:3072
	s_add_u32 s22, s28, 0x160000
	s_addc_u32 s23, s29, 0
	s_mov_b32 m0, s30
	v_lshl_add_u64 v[212:213], s[22:23], 0, v[198:199]
	ds_read_b128 v[162:165], v249 offset:32768
	ds_read_b128 v[166:169], v249 offset:33792
	ds_read_b128 v[170:173], v249 offset:34816
	ds_read_b128 v[174:177], v249 offset:35840
	ds_read_b128 v[178:181], v249 offset:36864
	ds_read_b128 v[182:185], v249 offset:37888
	ds_read_b128 v[186:189], v249 offset:38912
	ds_read_b128 v[190:193], v249 offset:39936
	global_load_lds_dwordx4 v[212:213], off
	v_lshl_add_u64 v[212:213], s[22:23], 0, v[196:197]
	s_mov_b32 m0, s31
	s_nop 0
	global_load_lds_dwordx4 v[212:213], off
	s_waitcnt vmcnt(8)
	s_waitcnt lgkmcnt(0)
	s_setprio 1
	s_barrier
	v_mfma_f32_16x16x32_bf16 v[150:153], v[90:93], v[162:165], v[150:153]
	v_mfma_f32_16x16x32_bf16 v[150:153], v[102:105], v[166:169], v[150:153]
	v_mfma_f32_16x16x32_bf16 v[146:149], v[114:117], v[162:165], v[146:149]
	v_mfma_f32_16x16x32_bf16 v[146:149], v[126:129], v[166:169], v[146:149]
	v_mfma_f32_16x16x32_bf16 v[118:121], v[114:117], v[170:173], v[118:121]
	v_mfma_f32_16x16x32_bf16 v[118:121], v[126:129], v[174:177], v[118:121]
	v_mfma_f32_16x16x32_bf16 v[122:125], v[90:93], v[170:173], v[122:125]
	v_mfma_f32_16x16x32_bf16 v[122:125], v[102:105], v[174:177], v[122:125]
	v_mfma_f32_16x16x32_bf16 v[98:101], v[90:93], v[178:181], v[98:101]
	v_mfma_f32_16x16x32_bf16 v[98:101], v[102:105], v[182:185], v[98:101]
	v_mfma_f32_16x16x32_bf16 v[94:97], v[114:117], v[178:181], v[94:97]
	v_mfma_f32_16x16x32_bf16 v[94:97], v[126:129], v[182:185], v[94:97]
	v_mfma_f32_16x16x32_bf16 v[74:77], v[114:117], v[186:189], v[74:77]
	v_mfma_f32_16x16x32_bf16 v[74:77], v[126:129], v[190:193], v[74:77]
	v_mfma_f32_16x16x32_bf16 v[78:81], v[90:93], v[186:189], v[78:81]
	v_mfma_f32_16x16x32_bf16 v[78:81], v[102:105], v[190:193], v[78:81]
	v_mfma_f32_16x16x32_bf16 v[134:137], v[138:141], v[162:165], v[134:137]
	v_mfma_f32_16x16x32_bf16 v[134:137], v[142:145], v[166:169], v[134:137]
	v_mfma_f32_16x16x32_bf16 v[130:133], v[154:157], v[162:165], v[130:133]
	v_mfma_f32_16x16x32_bf16 v[130:133], v[158:161], v[166:169], v[130:133]
	v_mfma_f32_16x16x32_bf16 v[106:109], v[154:157], v[170:173], v[106:109]
	v_mfma_f32_16x16x32_bf16 v[106:109], v[158:161], v[174:177], v[106:109]
	v_mfma_f32_16x16x32_bf16 v[110:113], v[138:141], v[170:173], v[110:113]
	v_mfma_f32_16x16x32_bf16 v[110:113], v[142:145], v[174:177], v[110:113]
	v_mfma_f32_16x16x32_bf16 v[86:89], v[138:141], v[178:181], v[86:89]
	v_mfma_f32_16x16x32_bf16 v[86:89], v[142:145], v[182:185], v[86:89]
	v_mfma_f32_16x16x32_bf16 v[82:85], v[154:157], v[178:181], v[82:85]
	v_mfma_f32_16x16x32_bf16 v[82:85], v[158:161], v[182:185], v[82:85]
	v_mfma_f32_16x16x32_bf16 v[66:69], v[154:157], v[186:189], v[66:69]
	v_mfma_f32_16x16x32_bf16 v[66:69], v[158:161], v[190:193], v[66:69]
	v_mfma_f32_16x16x32_bf16 v[70:73], v[138:141], v[186:189], v[70:73]
	v_mfma_f32_16x16x32_bf16 v[70:73], v[142:145], v[190:193], v[70:73]
	s_setprio 0
	s_barrier
; #define PG8_STAGE(bufoff, gbase, voff) do { _Pragma("unroll") for (int _i = 0; _i < 2; ++_i) \
;         __builtin_amdgcn_global_load_lds((const unsigned*)((const char*)(gbase) + (voff)[_i]), (LAS unsigned*)(lds + (bufoff) + ldsw + _i * 8192), 16, 0, 0); } while (0)
; #define PG8_LDA(dst, b, h) do { _Pragma("unroll") for (int m = 0; m < 4; ++m) _Pragma("unroll") for (int k = 0; k < 2; ++k) dst[m][k] = *(const LAS bf16x8*)(lds + PG8_SA(b, h) + aoff + m * 2048 + k * 1024); } while (0)
; #define PG8_MMA(ai, bj, At, Bt) do { __builtin_amdgcn_s_setprio(1); _Pragma("unroll") for (int m = 0; m < 4; ++m) _Pragma("unroll") for (int n = 0; n < 2; ++n) _Pragma("unroll") for (int k = 0; k < 2; ++k) \
;         acc[ai][bj][m][n] = __builtin_amdgcn_mfma_f32_16x16x32_bf16(Bt[n][k], At[m][k], acc[ai][bj][m][n], 0, 0, 0); __builtin_amdgcn_s_setprio(0); } while (0)
; #define PG8_WAIT_V(n) asm volatile("s_waitcnt vmcnt(" #n ")" ::: "memory")
; #define PG8_WAIT_L(n) asm volatile("s_waitcnt lgkmcnt(" #n ")" ::: "memory")
; #define PG8_BAR __builtin_amdgcn_s_barrier()
; #define PG8_SCHED __builtin_amdgcn_sched_barrier(0)
; template <class Epi, class Sched, bool ALIGN_EPI = false, bool SP2 = false>
; __device__ __forceinline__ void gemm_phase(LAS unsigned char* lds, const Gemm g, const Sched& S, const Epi& E) {
;     ...
;             PG8_WAIT_V(8); PG8_WAIT_L(0); PG8_BAR; PG8_MMA(0, 0, At, B0); PG8_MMA(0, 1, At, B1); PG8_BAR; PG8_SCHED;
;             PG8_LDA(At, 1, 1); PG8_STAGE(PG8_SB(1, 0), b3, voffB); PG8_STAGE(PG8_SB(1, 1), b3 + hstep, voffB); PG8_STAGE(PG8_SA(1, 0), a3, voffA);
;             PG8_WAIT_V(8); PG8_WAIT_L(0); PG8_BAR; PG8_MMA(1, 0, At, B0); PG8_MMA(1, 1, At, B1); PG8_BAR; PG8_SCHED;
;     ...
;         if constexpr (ALIGN_EPI) { if (wr == 0) PG8_BAR; }
	s_add_i32 s22, s49, s7
	v_lshl_add_u64 v[204:205], v[204:205], 0, s[12:13]
	s_mov_b32 m0, s22
	ds_read_b128 v[162:165], v249 offset:49152
	ds_read_b128 v[166:169], v249 offset:50176
	ds_read_b128 v[170:173], v249 offset:51200
	ds_read_b128 v[174:177], v249 offset:52224
	ds_read_b128 v[178:181], v249 offset:53248
	ds_read_b128 v[182:185], v249 offset:54272
	ds_read_b128 v[186:189], v249 offset:55296
	ds_read_b128 v[190:193], v249 offset:56320
	global_load_lds_dwordx4 v[204:205], off
	s_add_i32 m0, s22, 0x2000
	s_add_u32 s22, s26, 0x160080
	v_lshl_add_u64 v[204:205], v[206:207], 0, s[12:13]
	s_addc_u32 s23, s27, 0
	s_add_i32 s26, s50, s7
	global_load_lds_dwordx4 v[204:205], off
	v_lshl_add_u64 v[204:205], s[22:23], 0, v[0:1]
	s_mov_b32 m0, s26
	s_nop 0
	global_load_lds_dwordx4 v[204:205], off
	v_lshl_add_u64 v[204:205], s[22:23], 0, v[194:195]
	s_add_i32 m0, s26, 0x2000
	s_nop 0
	global_load_lds_dwordx4 v[204:205], off
	v_lshl_add_u64 v[204:205], v[208:209], 0, s[12:13]
	s_mov_b32 m0, s35
	s_nop 0
	global_load_lds_dwordx4 v[204:205], off
	v_lshl_add_u64 v[204:205], v[210:211], 0, s[12:13]
	s_mov_b32 m0, s40
	s_nop 0
	global_load_lds_dwordx4 v[204:205], off
	s_waitcnt vmcnt(8)
	s_waitcnt lgkmcnt(0)
	s_setprio 1
	s_barrier
	v_mfma_f32_16x16x32_bf16 v[62:65], v[90:93], v[162:165], v[62:65]
	v_mfma_f32_16x16x32_bf16 v[62:65], v[102:105], v[166:169], v[62:65]
	v_mfma_f32_16x16x32_bf16 v[58:61], v[114:117], v[162:165], v[58:61]
	v_mfma_f32_16x16x32_bf16 v[58:61], v[126:129], v[166:169], v[58:61]
	v_mfma_f32_16x16x32_bf16 v[42:45], v[114:117], v[170:173], v[42:45]
	v_mfma_f32_16x16x32_bf16 v[42:45], v[126:129], v[174:177], v[42:45]
	v_mfma_f32_16x16x32_bf16 v[46:49], v[90:93], v[170:173], v[46:49]
	v_mfma_f32_16x16x32_bf16 v[46:49], v[102:105], v[174:177], v[46:49]
	v_mfma_f32_16x16x32_bf16 v[30:33], v[90:93], v[178:181], v[30:33]
	v_mfma_f32_16x16x32_bf16 v[30:33], v[102:105], v[182:185], v[30:33]
	v_mfma_f32_16x16x32_bf16 v[26:29], v[114:117], v[178:181], v[26:29]
	v_mfma_f32_16x16x32_bf16 v[26:29], v[126:129], v[182:185], v[26:29]
	v_mfma_f32_16x16x32_bf16 v[10:13], v[114:117], v[186:189], v[10:13]
	v_mfma_f32_16x16x32_bf16 v[10:13], v[126:129], v[190:193], v[10:13]
	v_mfma_f32_16x16x32_bf16 v[14:17], v[90:93], v[186:189], v[14:17]
	v_mfma_f32_16x16x32_bf16 v[14:17], v[102:105], v[190:193], v[14:17]
	v_mfma_f32_16x16x32_bf16 v[54:57], v[138:141], v[162:165], v[54:57]
	v_mfma_f32_16x16x32_bf16 v[54:57], v[142:145], v[166:169], v[54:57]
	v_mfma_f32_16x16x32_bf16 v[50:53], v[154:157], v[162:165], v[50:53]
	v_mfma_f32_16x16x32_bf16 v[50:53], v[158:161], v[166:169], v[50:53]
	v_mfma_f32_16x16x32_bf16 v[34:37], v[154:157], v[170:173], v[34:37]
	v_mfma_f32_16x16x32_bf16 v[34:37], v[158:161], v[174:177], v[34:37]
	v_mfma_f32_16x16x32_bf16 v[38:41], v[138:141], v[170:173], v[38:41]
	v_mfma_f32_16x16x32_bf16 v[38:41], v[142:145], v[174:177], v[38:41]
	v_mfma_f32_16x16x32_bf16 v[22:25], v[138:141], v[178:181], v[22:25]
	v_mfma_f32_16x16x32_bf16 v[22:25], v[142:145], v[182:185], v[22:25]
	v_mfma_f32_16x16x32_bf16 v[18:21], v[154:157], v[178:181], v[18:21]
	v_mfma_f32_16x16x32_bf16 v[18:21], v[158:161], v[182:185], v[18:21]
	v_mfma_f32_16x16x32_bf16 v[2:5], v[154:157], v[186:189], v[2:5]
	v_mfma_f32_16x16x32_bf16 v[2:5], v[158:161], v[190:193], v[2:5]
	v_mfma_f32_16x16x32_bf16 v[6:9], v[138:141], v[186:189], v[6:9]
	v_mfma_f32_16x16x32_bf16 v[6:9], v[142:145], v[190:193], v[6:9]
	s_setprio 0
	s_barrier
	s_add_i32 s48, s48, 2
	s_add_u32 s46, s46, 0x100
	s_addc_u32 s47, s47, 0
	s_cmpk_gt_u32 s48, 0x55
	s_mov_b64 s[22:23], s[24:25]
	s_cbranch_scc0 .LBB0_1007
	s_and_b64 vcc, exec, s[18:19]
	s_cbranch_vccz .LBB0_1010
	s_barrier
